# GEMM K-loops: back edge rotated - counter and next-iteration scalar address set-up moved in front of the closing barrier
# baseline (speedup 1.0000x reference)
.Lg1k_body:
	v_add_u32_e32 v146, s73, v166
	ds_read_b128 v[148:151], v146
	ds_read_b128 v[152:155], v146 offset:1024
	ds_read_b128 v[156:159], v146 offset:2048
	ds_read_b128 v[160:163], v146 offset:3072
	v_add_u32_e32 v146, s76, v166
	ds_read_b128 v[172:175], v146
	ds_read_b128 v[176:179], v146 offset:1024
	ds_read_b128 v[180:183], v146 offset:2048
	ds_read_b128 v[184:187], v146 offset:3072
	s_cmpk_eq_i32 s10, 0x700
	s_cselect_b32 s29, s69, s29
	s_cselect_b32 s28, s68, s28
	s_cselect_b32 s31, s21, s31
	s_cselect_b32 s30, s59, s30
	s_cselect_b32 s35, s23, s35
	s_cselect_b32 s34, s58, s34
	v_lshl_add_u64 v[164:165], v[142:143], 0, s[10:11]
	s_add_i32 m0, s41, 0xc000
	ds_read_b128 v[188:191], v171
	ds_read_b128 v[202:205], v171 offset:1024
	ds_read_b128 v[206:209], v171 offset:2048
	ds_read_b128 v[210:213], v171 offset:3072
	ds_read_b128 v[214:217], v171 offset:4096
	ds_read_b128 v[218:221], v171 offset:5120
	ds_read_b128 v[222:225], v171 offset:6144
	ds_read_b128 v[226:229], v171 offset:7168
	global_load_lds_dwordx4 v[164:165], off
	v_lshl_add_u64 v[164:165], v[144:145], 0, s[10:11]
	s_add_i32 m0, s41, 0xe000
	s_nop 0
	global_load_lds_dwordx4 v[164:165], off
	s_waitcnt vmcnt(8)
	s_waitcnt lgkmcnt(0)
	s_barrier
	s_setprio 1
	s_waitcnt lgkmcnt(0)
	v_mfma_f32_16x16x32_bf16 v[126:129], v[148:151], v[188:191], v[126:129]
	v_mfma_f32_16x16x32_bf16 v[122:125], v[156:159], v[188:191], v[122:125]
	v_mfma_f32_16x16x32_bf16 v[110:113], v[148:151], v[206:209], v[110:113]
	v_mfma_f32_16x16x32_bf16 v[106:109], v[156:159], v[206:209], v[106:109]
	v_mfma_f32_16x16x32_bf16 v[94:97], v[148:151], v[214:217], v[94:97]
	v_mfma_f32_16x16x32_bf16 v[90:93], v[156:159], v[214:217], v[90:93]
	v_mfma_f32_16x16x32_bf16 v[78:81], v[148:151], v[222:225], v[78:81]
	v_mfma_f32_16x16x32_bf16 v[74:77], v[156:159], v[222:225], v[74:77]
	v_mfma_f32_16x16x32_bf16 v[126:129], v[152:155], v[202:205], v[126:129]
	v_mfma_f32_16x16x32_bf16 v[122:125], v[160:163], v[202:205], v[122:125]
	v_mfma_f32_16x16x32_bf16 v[110:113], v[152:155], v[210:213], v[110:113]
	v_mfma_f32_16x16x32_bf16 v[106:109], v[160:163], v[210:213], v[106:109]
	v_mfma_f32_16x16x32_bf16 v[94:97], v[152:155], v[218:221], v[94:97]
	v_mfma_f32_16x16x32_bf16 v[90:93], v[160:163], v[218:221], v[90:93]
	v_mfma_f32_16x16x32_bf16 v[78:81], v[152:155], v[226:229], v[78:81]
	v_mfma_f32_16x16x32_bf16 v[74:77], v[160:163], v[226:229], v[74:77]
	s_setprio 0
	s_setprio 1
	v_mfma_f32_16x16x32_bf16 v[118:121], v[172:175], v[188:191], v[118:121]
	v_mfma_f32_16x16x32_bf16 v[114:117], v[180:183], v[188:191], v[114:117]
	v_mfma_f32_16x16x32_bf16 v[102:105], v[172:175], v[206:209], v[102:105]
	v_mfma_f32_16x16x32_bf16 v[98:101], v[180:183], v[206:209], v[98:101]
	v_mfma_f32_16x16x32_bf16 v[86:89], v[172:175], v[214:217], v[86:89]
	v_mfma_f32_16x16x32_bf16 v[82:85], v[180:183], v[214:217], v[82:85]
	v_mfma_f32_16x16x32_bf16 v[70:73], v[172:175], v[222:225], v[70:73]
	v_mfma_f32_16x16x32_bf16 v[66:69], v[180:183], v[222:225], v[66:69]
	v_mfma_f32_16x16x32_bf16 v[118:121], v[176:179], v[202:205], v[118:121]
	v_mfma_f32_16x16x32_bf16 v[114:117], v[184:187], v[202:205], v[114:117]
	v_mfma_f32_16x16x32_bf16 v[102:105], v[176:179], v[210:213], v[102:105]
	v_mfma_f32_16x16x32_bf16 v[98:101], v[184:187], v[210:213], v[98:101]
	v_mfma_f32_16x16x32_bf16 v[86:89], v[176:179], v[218:221], v[86:89]
	v_mfma_f32_16x16x32_bf16 v[82:85], v[184:187], v[218:221], v[82:85]
	v_mfma_f32_16x16x32_bf16 v[70:73], v[176:179], v[226:229], v[70:73]
	v_mfma_f32_16x16x32_bf16 v[66:69], v[184:187], v[226:229], v[66:69]
	s_setprio 0
	s_barrier
	s_add_i32 s73, s73, s40
	v_lshl_add_u64 v[164:165], s[30:31], 0, v[134:135]
	s_mov_b32 m0, s73
	ds_read_b128 v[188:191], v171 offset:16384
	ds_read_b128 v[202:205], v171 offset:17408
	ds_read_b128 v[206:209], v171 offset:18432
	ds_read_b128 v[210:213], v171 offset:19456
	ds_read_b128 v[214:217], v171 offset:20480
	ds_read_b128 v[218:221], v171 offset:21504
	ds_read_b128 v[222:225], v171 offset:22528
	ds_read_b128 v[226:229], v171 offset:23552
	global_load_lds_dwordx4 v[164:165], off
	s_add_i32 m0, s73, 0x2000
	s_add_u32 s74, s30, 0x40000
	v_lshl_add_u64 v[192:193], s[30:31], 0, v[130:131]
	s_addc_u32 s75, s31, 0
	s_add_i32 s73, s76, s40
	global_load_lds_dwordx4 v[192:193], off
	v_lshl_add_u64 v[194:195], s[74:75], 0, v[134:135]
	s_mov_b32 m0, s73
	s_nop 0
	global_load_lds_dwordx4 v[194:195], off
	v_lshl_add_u64 v[194:195], s[74:75], 0, v[130:131]
	s_add_i32 m0, s73, 0x2000
	s_nop 0
	global_load_lds_dwordx4 v[194:195], off
	v_lshl_add_u64 v[194:195], s[34:35], 0, v[136:137]
	s_mov_b32 m0, s41
	s_nop 0
	global_load_lds_dwordx4 v[194:195], off
	v_lshl_add_u64 v[194:195], s[34:35], 0, v[132:133]
	s_mov_b32 m0, s42
	s_nop 0
	global_load_lds_dwordx4 v[194:195], off
	s_waitcnt vmcnt(8)
	s_waitcnt lgkmcnt(0)
	s_barrier
	s_setprio 1
	s_waitcnt lgkmcnt(0)
	v_mfma_f32_16x16x32_bf16 v[62:65], v[148:151], v[188:191], v[62:65]
	v_mfma_f32_16x16x32_bf16 v[58:61], v[156:159], v[188:191], v[58:61]
	v_mfma_f32_16x16x32_bf16 v[46:49], v[148:151], v[206:209], v[46:49]
	v_mfma_f32_16x16x32_bf16 v[42:45], v[156:159], v[206:209], v[42:45]
	v_mfma_f32_16x16x32_bf16 v[30:33], v[148:151], v[214:217], v[30:33]
	v_mfma_f32_16x16x32_bf16 v[26:29], v[156:159], v[214:217], v[26:29]
	v_mfma_f32_16x16x32_bf16 v[14:17], v[148:151], v[222:225], v[14:17]
	v_mfma_f32_16x16x32_bf16 v[10:13], v[156:159], v[222:225], v[10:13]
	v_mfma_f32_16x16x32_bf16 v[62:65], v[152:155], v[202:205], v[62:65]
	v_mfma_f32_16x16x32_bf16 v[58:61], v[160:163], v[202:205], v[58:61]
	v_mfma_f32_16x16x32_bf16 v[46:49], v[152:155], v[210:213], v[46:49]
	v_mfma_f32_16x16x32_bf16 v[42:45], v[160:163], v[210:213], v[42:45]
	v_mfma_f32_16x16x32_bf16 v[30:33], v[152:155], v[218:221], v[30:33]
	v_mfma_f32_16x16x32_bf16 v[26:29], v[160:163], v[218:221], v[26:29]
	v_mfma_f32_16x16x32_bf16 v[14:17], v[152:155], v[226:229], v[14:17]
	v_mfma_f32_16x16x32_bf16 v[10:13], v[160:163], v[226:229], v[10:13]
	s_setprio 0
	s_setprio 1
	v_mfma_f32_16x16x32_bf16 v[54:57], v[172:175], v[188:191], v[54:57]
	v_mfma_f32_16x16x32_bf16 v[50:53], v[180:183], v[188:191], v[50:53]
	v_mfma_f32_16x16x32_bf16 v[38:41], v[172:175], v[206:209], v[38:41]
	v_mfma_f32_16x16x32_bf16 v[34:37], v[180:183], v[206:209], v[34:37]
	v_mfma_f32_16x16x32_bf16 v[22:25], v[172:175], v[214:217], v[22:25]
	v_mfma_f32_16x16x32_bf16 v[18:21], v[180:183], v[214:217], v[18:21]
	v_mfma_f32_16x16x32_bf16 v[6:9], v[172:175], v[222:225], v[6:9]
	v_mfma_f32_16x16x32_bf16 v[2:5], v[180:183], v[222:225], v[2:5]
	v_mfma_f32_16x16x32_bf16 v[54:57], v[176:179], v[202:205], v[54:57]
	v_mfma_f32_16x16x32_bf16 v[50:53], v[184:187], v[202:205], v[50:53]
	v_mfma_f32_16x16x32_bf16 v[38:41], v[176:179], v[210:213], v[38:41]
	v_mfma_f32_16x16x32_bf16 v[34:37], v[184:187], v[210:213], v[34:37]
	v_mfma_f32_16x16x32_bf16 v[22:25], v[176:179], v[218:221], v[22:25]
	v_mfma_f32_16x16x32_bf16 v[18:21], v[184:187], v[218:221], v[18:21]
	v_mfma_f32_16x16x32_bf16 v[6:9], v[176:179], v[226:229], v[6:9]
	v_mfma_f32_16x16x32_bf16 v[2:5], v[184:187], v[226:229], v[2:5]
	s_setprio 0
	s_barrier
	s_add_i32 s73, 0, 0x18000
	v_add_u32_e32 v146, s73, v166
	s_add_i32 s74, 0, 0x1c000
	ds_read_b128 v[148:151], v146
	ds_read_b128 v[152:155], v146 offset:1024
	ds_read_b128 v[156:159], v146 offset:2048
	ds_read_b128 v[160:163], v146 offset:3072
	v_add_u32_e32 v146, s74, v166
	ds_read_b128 v[172:175], v146
	ds_read_b128 v[176:179], v146 offset:1024
	ds_read_b128 v[180:183], v146 offset:2048
	ds_read_b128 v[184:187], v146 offset:3072
	s_add_u32 s34, s34, 0x40000
	s_addc_u32 s35, s35, 0
	s_mov_b32 m0, s43
	v_lshl_add_u64 v[194:195], s[34:35], 0, v[136:137]
	ds_read_b128 v[188:191], v171 offset:32768
	ds_read_b128 v[202:205], v171 offset:33792
	ds_read_b128 v[206:209], v171 offset:34816
	ds_read_b128 v[210:213], v171 offset:35840
	ds_read_b128 v[214:217], v171 offset:36864
	ds_read_b128 v[218:221], v171 offset:37888
	ds_read_b128 v[222:225], v171 offset:38912
	ds_read_b128 v[226:229], v171 offset:39936
	global_load_lds_dwordx4 v[194:195], off
	v_lshl_add_u64 v[194:195], s[34:35], 0, v[132:133]
	s_mov_b32 m0, s44
	s_nop 0
	global_load_lds_dwordx4 v[194:195], off
	s_waitcnt vmcnt(8)
	s_waitcnt lgkmcnt(0)
	s_barrier
	s_setprio 1
	s_waitcnt lgkmcnt(0)
	v_mfma_f32_16x16x32_bf16 v[126:129], v[148:151], v[188:191], v[126:129]
	v_mfma_f32_16x16x32_bf16 v[122:125], v[156:159], v[188:191], v[122:125]
	v_mfma_f32_16x16x32_bf16 v[110:113], v[148:151], v[206:209], v[110:113]
	v_mfma_f32_16x16x32_bf16 v[106:109], v[156:159], v[206:209], v[106:109]
	v_mfma_f32_16x16x32_bf16 v[94:97], v[148:151], v[214:217], v[94:97]
	v_mfma_f32_16x16x32_bf16 v[90:93], v[156:159], v[214:217], v[90:93]
	v_mfma_f32_16x16x32_bf16 v[78:81], v[148:151], v[222:225], v[78:81]
	v_mfma_f32_16x16x32_bf16 v[74:77], v[156:159], v[222:225], v[74:77]
	v_mfma_f32_16x16x32_bf16 v[126:129], v[152:155], v[202:205], v[126:129]
	v_mfma_f32_16x16x32_bf16 v[122:125], v[160:163], v[202:205], v[122:125]
	v_mfma_f32_16x16x32_bf16 v[110:113], v[152:155], v[210:213], v[110:113]
	v_mfma_f32_16x16x32_bf16 v[106:109], v[160:163], v[210:213], v[106:109]
	v_mfma_f32_16x16x32_bf16 v[94:97], v[152:155], v[218:221], v[94:97]
	v_mfma_f32_16x16x32_bf16 v[90:93], v[160:163], v[218:221], v[90:93]
	v_mfma_f32_16x16x32_bf16 v[78:81], v[152:155], v[226:229], v[78:81]
	v_mfma_f32_16x16x32_bf16 v[74:77], v[160:163], v[226:229], v[74:77]
	s_setprio 0
	s_setprio 1
	v_mfma_f32_16x16x32_bf16 v[118:121], v[172:175], v[188:191], v[118:121]
	v_mfma_f32_16x16x32_bf16 v[114:117], v[180:183], v[188:191], v[114:117]
	v_mfma_f32_16x16x32_bf16 v[102:105], v[172:175], v[206:209], v[102:105]
	v_mfma_f32_16x16x32_bf16 v[98:101], v[180:183], v[206:209], v[98:101]
	v_mfma_f32_16x16x32_bf16 v[86:89], v[172:175], v[214:217], v[86:89]
	v_mfma_f32_16x16x32_bf16 v[82:85], v[180:183], v[214:217], v[82:85]
	v_mfma_f32_16x16x32_bf16 v[70:73], v[172:175], v[222:225], v[70:73]
	v_mfma_f32_16x16x32_bf16 v[66:69], v[180:183], v[222:225], v[66:69]
	v_mfma_f32_16x16x32_bf16 v[118:121], v[176:179], v[202:205], v[118:121]
	v_mfma_f32_16x16x32_bf16 v[114:117], v[184:187], v[202:205], v[114:117]
	v_mfma_f32_16x16x32_bf16 v[102:105], v[176:179], v[210:213], v[102:105]
	v_mfma_f32_16x16x32_bf16 v[98:101], v[184:187], v[210:213], v[98:101]
	v_mfma_f32_16x16x32_bf16 v[86:89], v[176:179], v[218:221], v[86:89]
	v_mfma_f32_16x16x32_bf16 v[82:85], v[184:187], v[218:221], v[82:85]
	v_mfma_f32_16x16x32_bf16 v[70:73], v[176:179], v[226:229], v[70:73]
	v_mfma_f32_16x16x32_bf16 v[66:69], v[184:187], v[226:229], v[66:69]
	s_setprio 0
	s_barrier
	s_add_i32 s34, s73, s40
	v_lshl_add_u64 v[164:165], v[164:165], 0, s[90:91]
	s_mov_b32 m0, s34
	ds_read_b128 v[188:191], v171 offset:49152
	ds_read_b128 v[202:205], v171 offset:50176
	ds_read_b128 v[206:209], v171 offset:51200
	ds_read_b128 v[210:213], v171 offset:52224
	ds_read_b128 v[214:217], v171 offset:53248
	ds_read_b128 v[218:221], v171 offset:54272
	ds_read_b128 v[222:225], v171 offset:55296
	ds_read_b128 v[226:229], v171 offset:56320
	global_load_lds_dwordx4 v[164:165], off
	s_add_i32 m0, s34, 0x2000
	s_add_u32 s30, s30, 0x40080
	v_lshl_add_u64 v[164:165], v[192:193], 0, s[90:91]
	s_addc_u32 s31, s31, 0
	s_add_i32 s34, s74, s40
	global_load_lds_dwordx4 v[164:165], off
	v_lshl_add_u64 v[164:165], s[30:31], 0, v[134:135]
	s_mov_b32 m0, s34
	s_nop 0
	global_load_lds_dwordx4 v[164:165], off
	v_lshl_add_u64 v[164:165], s[30:31], 0, v[130:131]
	s_add_i32 m0, s34, 0x2000
	s_nop 0
	global_load_lds_dwordx4 v[164:165], off
	v_lshl_add_u64 v[164:165], s[28:29], 0, v[136:137]
	s_mov_b32 m0, s45
	s_nop 0
	global_load_lds_dwordx4 v[164:165], off
	v_lshl_add_u64 v[164:165], s[28:29], 0, v[132:133]
	s_mov_b32 m0, s51
	s_nop 0
	global_load_lds_dwordx4 v[164:165], off
	s_waitcnt vmcnt(8)
	s_waitcnt lgkmcnt(0)
	s_barrier
	s_setprio 1
	s_waitcnt lgkmcnt(0)
	v_mfma_f32_16x16x32_bf16 v[62:65], v[148:151], v[188:191], v[62:65]
	v_mfma_f32_16x16x32_bf16 v[58:61], v[156:159], v[188:191], v[58:61]
	v_mfma_f32_16x16x32_bf16 v[46:49], v[148:151], v[206:209], v[46:49]
	v_mfma_f32_16x16x32_bf16 v[42:45], v[156:159], v[206:209], v[42:45]
	v_mfma_f32_16x16x32_bf16 v[30:33], v[148:151], v[214:217], v[30:33]
	v_mfma_f32_16x16x32_bf16 v[26:29], v[156:159], v[214:217], v[26:29]
	v_mfma_f32_16x16x32_bf16 v[14:17], v[148:151], v[222:225], v[14:17]
	v_mfma_f32_16x16x32_bf16 v[10:13], v[156:159], v[222:225], v[10:13]
	v_mfma_f32_16x16x32_bf16 v[62:65], v[152:155], v[202:205], v[62:65]
	v_mfma_f32_16x16x32_bf16 v[58:61], v[160:163], v[202:205], v[58:61]
	v_mfma_f32_16x16x32_bf16 v[46:49], v[152:155], v[210:213], v[46:49]
	v_mfma_f32_16x16x32_bf16 v[42:45], v[160:163], v[210:213], v[42:45]
	v_mfma_f32_16x16x32_bf16 v[30:33], v[152:155], v[218:221], v[30:33]
	v_mfma_f32_16x16x32_bf16 v[26:29], v[160:163], v[218:221], v[26:29]
	v_mfma_f32_16x16x32_bf16 v[14:17], v[152:155], v[226:229], v[14:17]
	v_mfma_f32_16x16x32_bf16 v[10:13], v[160:163], v[226:229], v[10:13]
	s_setprio 0
	s_setprio 1
	v_mfma_f32_16x16x32_bf16 v[54:57], v[172:175], v[188:191], v[54:57]
	v_mfma_f32_16x16x32_bf16 v[50:53], v[180:183], v[188:191], v[50:53]
	v_mfma_f32_16x16x32_bf16 v[38:41], v[172:175], v[206:209], v[38:41]
	v_mfma_f32_16x16x32_bf16 v[34:37], v[180:183], v[206:209], v[34:37]
	v_mfma_f32_16x16x32_bf16 v[22:25], v[172:175], v[214:217], v[22:25]
	v_mfma_f32_16x16x32_bf16 v[18:21], v[180:183], v[214:217], v[18:21]
	v_mfma_f32_16x16x32_bf16 v[6:9], v[172:175], v[222:225], v[6:9]
	v_mfma_f32_16x16x32_bf16 v[2:5], v[180:183], v[222:225], v[2:5]
	v_mfma_f32_16x16x32_bf16 v[54:57], v[176:179], v[202:205], v[54:57]
	v_mfma_f32_16x16x32_bf16 v[50:53], v[184:187], v[202:205], v[50:53]
	v_mfma_f32_16x16x32_bf16 v[38:41], v[176:179], v[210:213], v[38:41]
	v_mfma_f32_16x16x32_bf16 v[34:37], v[184:187], v[210:213], v[34:37]
	v_mfma_f32_16x16x32_bf16 v[22:25], v[176:179], v[218:221], v[22:25]
	v_mfma_f32_16x16x32_bf16 v[18:21], v[184:187], v[218:221], v[18:21]
	v_mfma_f32_16x16x32_bf16 v[6:9], v[176:179], v[226:229], v[6:9]
	v_mfma_f32_16x16x32_bf16 v[2:5], v[184:187], v[226:229], v[2:5]
	s_setprio 0
	s_add_i32 s72, s72, 2
	s_add_u32 s10, s10, 0x100
	s_addc_u32 s11, s11, 0
	s_add_u32 s28, s8, s10
	s_addc_u32 s29, s9, s11
	s_add_u32 s34, s28, 0x100
	s_addc_u32 s35, s29, 0
	s_add_u32 s30, s70, s10
	s_addc_u32 s31, s71, s11
	s_add_u32 s28, s28, 0x180
	s_addc_u32 s29, s29, 0
	s_add_i32 s73, 0, 0x10000
	s_add_i32 s76, 0, 0x14000
	s_cmp_gt_u32 s72, 13
	s_barrier
	s_cbranch_scc0 .Lg1k_body
	s_and_b64 vcc, exec, s[18:19]
	s_cbranch_vccz .LBB0_134
	s_barrier

.Lkvk_body:
	v_add_u32_e32 v0, s85, v152
	ds_read_b128 v[148:151], v0
	ds_read_b128 v[154:157], v0 offset:1024
	ds_read_b128 v[158:161], v0 offset:2048
	ds_read_b128 v[162:165], v0 offset:3072
	v_add_u32_e32 v0, vcc_lo, v152
	ds_read_b128 v[166:169], v0
	ds_read_b128 v[170:173], v0 offset:1024
	ds_read_b128 v[174:177], v0 offset:2048
	ds_read_b128 v[178:181], v0 offset:3072
	s_cmpk_eq_i32 s30, 0x700
	s_cselect_b32 s35, s74, s35
	s_cselect_b32 s34, s73, s34
	s_cselect_b32 s37, s21, s37
	s_cselect_b32 s36, s72, s36
	s_cselect_b32 s39, s23, s39
	s_cselect_b32 s38, s71, s38
	v_lshl_add_u64 v[194:195], v[144:145], 0, s[30:31]
	s_add_i32 m0, s45, 0xc000
	ds_read_b128 v[182:185], v153
	ds_read_b128 v[186:189], v153 offset:1024
	ds_read_b128 v[190:193], v153 offset:2048
	ds_read_b128 v[202:205], v153 offset:3072
	ds_read_b128 v[206:209], v153 offset:4096
	ds_read_b128 v[210:213], v153 offset:5120
	ds_read_b128 v[214:217], v153 offset:6144
	ds_read_b128 v[218:221], v153 offset:7168
	global_load_lds_dwordx4 v[194:195], off
	v_lshl_add_u64 v[194:195], v[146:147], 0, s[30:31]
	s_add_i32 m0, s45, 0xe000
	s_nop 0
	global_load_lds_dwordx4 v[194:195], off
	s_waitcnt vmcnt(8)
	s_waitcnt lgkmcnt(0)
	s_barrier
	s_setprio 1
	s_waitcnt lgkmcnt(0)
	v_mfma_f32_16x16x32_bf16 v[126:129], v[148:151], v[182:185], v[126:129]
	v_mfma_f32_16x16x32_bf16 v[122:125], v[158:161], v[182:185], v[122:125]
	v_mfma_f32_16x16x32_bf16 v[110:113], v[148:151], v[190:193], v[110:113]
	v_mfma_f32_16x16x32_bf16 v[106:109], v[158:161], v[190:193], v[106:109]
	v_mfma_f32_16x16x32_bf16 v[94:97], v[148:151], v[206:209], v[94:97]
	v_mfma_f32_16x16x32_bf16 v[90:93], v[158:161], v[206:209], v[90:93]
	v_mfma_f32_16x16x32_bf16 v[78:81], v[148:151], v[214:217], v[78:81]
	v_mfma_f32_16x16x32_bf16 v[74:77], v[158:161], v[214:217], v[74:77]
	v_mfma_f32_16x16x32_bf16 v[126:129], v[154:157], v[186:189], v[126:129]
	v_mfma_f32_16x16x32_bf16 v[122:125], v[162:165], v[186:189], v[122:125]
	v_mfma_f32_16x16x32_bf16 v[110:113], v[154:157], v[202:205], v[110:113]
	v_mfma_f32_16x16x32_bf16 v[106:109], v[162:165], v[202:205], v[106:109]
	v_mfma_f32_16x16x32_bf16 v[94:97], v[154:157], v[210:213], v[94:97]
	v_mfma_f32_16x16x32_bf16 v[90:93], v[162:165], v[210:213], v[90:93]
	v_mfma_f32_16x16x32_bf16 v[78:81], v[154:157], v[218:221], v[78:81]
	v_mfma_f32_16x16x32_bf16 v[74:77], v[162:165], v[218:221], v[74:77]
	s_setprio 0
	s_setprio 1
	v_mfma_f32_16x16x32_bf16 v[118:121], v[166:169], v[182:185], v[118:121]
	v_mfma_f32_16x16x32_bf16 v[114:117], v[174:177], v[182:185], v[114:117]
	v_mfma_f32_16x16x32_bf16 v[102:105], v[166:169], v[190:193], v[102:105]
	v_mfma_f32_16x16x32_bf16 v[98:101], v[174:177], v[190:193], v[98:101]
	v_mfma_f32_16x16x32_bf16 v[86:89], v[166:169], v[206:209], v[86:89]
	v_mfma_f32_16x16x32_bf16 v[82:85], v[174:177], v[206:209], v[82:85]
	v_mfma_f32_16x16x32_bf16 v[70:73], v[166:169], v[214:217], v[70:73]
	v_mfma_f32_16x16x32_bf16 v[66:69], v[174:177], v[214:217], v[66:69]
	v_mfma_f32_16x16x32_bf16 v[118:121], v[170:173], v[186:189], v[118:121]
	v_mfma_f32_16x16x32_bf16 v[114:117], v[178:181], v[186:189], v[114:117]
	v_mfma_f32_16x16x32_bf16 v[102:105], v[170:173], v[202:205], v[102:105]
	v_mfma_f32_16x16x32_bf16 v[98:101], v[178:181], v[202:205], v[98:101]
	v_mfma_f32_16x16x32_bf16 v[86:89], v[170:173], v[210:213], v[86:89]
	v_mfma_f32_16x16x32_bf16 v[82:85], v[178:181], v[210:213], v[82:85]
	v_mfma_f32_16x16x32_bf16 v[70:73], v[170:173], v[218:221], v[70:73]
	v_mfma_f32_16x16x32_bf16 v[66:69], v[178:181], v[218:221], v[66:69]
	s_setprio 0
	s_barrier
	s_add_i32 s85, s85, s44
	v_lshl_add_u64 v[194:195], s[36:37], 0, v[134:135]
	s_mov_b32 m0, s85
	ds_read_b128 v[182:185], v153 offset:16384
	ds_read_b128 v[186:189], v153 offset:17408
	ds_read_b128 v[190:193], v153 offset:18432
	ds_read_b128 v[202:205], v153 offset:19456
	ds_read_b128 v[206:209], v153 offset:20480
	ds_read_b128 v[210:213], v153 offset:21504
	ds_read_b128 v[214:217], v153 offset:22528
	ds_read_b128 v[218:221], v153 offset:23552
	global_load_lds_dwordx4 v[194:195], off
	s_add_i32 m0, s85, 0x2000
	s_add_u32 s86, s36, 0x40000
	v_lshl_add_u64 v[198:199], s[36:37], 0, v[130:131]
	s_addc_u32 s87, s37, 0
	s_add_i32 s85, vcc_lo, s44
	global_load_lds_dwordx4 v[198:199], off
	v_lshl_add_u64 v[222:223], s[86:87], 0, v[134:135]
	s_mov_b32 m0, s85
	s_nop 0
	global_load_lds_dwordx4 v[222:223], off
	v_lshl_add_u64 v[222:223], s[86:87], 0, v[130:131]
	s_add_i32 m0, s85, 0x2000
	s_nop 0
	global_load_lds_dwordx4 v[222:223], off
	v_lshl_add_u64 v[222:223], s[38:39], 0, v[136:137]
	s_mov_b32 m0, s45
	s_nop 0
	global_load_lds_dwordx4 v[222:223], off
	v_lshl_add_u64 v[222:223], s[38:39], 0, v[132:133]
	s_mov_b32 m0, s51
	s_nop 0
	global_load_lds_dwordx4 v[222:223], off
	s_waitcnt vmcnt(8)
	s_waitcnt lgkmcnt(0)
	s_barrier
	s_setprio 1
	s_waitcnt lgkmcnt(0)
	v_mfma_f32_16x16x32_bf16 v[62:65], v[148:151], v[182:185], v[62:65]
	v_mfma_f32_16x16x32_bf16 v[58:61], v[158:161], v[182:185], v[58:61]
	v_mfma_f32_16x16x32_bf16 v[46:49], v[148:151], v[190:193], v[46:49]
	v_mfma_f32_16x16x32_bf16 v[42:45], v[158:161], v[190:193], v[42:45]
	v_mfma_f32_16x16x32_bf16 v[30:33], v[148:151], v[206:209], v[30:33]
	v_mfma_f32_16x16x32_bf16 v[26:29], v[158:161], v[206:209], v[26:29]
	v_mfma_f32_16x16x32_bf16 v[14:17], v[148:151], v[214:217], v[14:17]
	v_mfma_f32_16x16x32_bf16 v[10:13], v[158:161], v[214:217], v[10:13]
	v_mfma_f32_16x16x32_bf16 v[62:65], v[154:157], v[186:189], v[62:65]
	v_mfma_f32_16x16x32_bf16 v[58:61], v[162:165], v[186:189], v[58:61]
	v_mfma_f32_16x16x32_bf16 v[46:49], v[154:157], v[202:205], v[46:49]
	v_mfma_f32_16x16x32_bf16 v[42:45], v[162:165], v[202:205], v[42:45]
	v_mfma_f32_16x16x32_bf16 v[30:33], v[154:157], v[210:213], v[30:33]
	v_mfma_f32_16x16x32_bf16 v[26:29], v[162:165], v[210:213], v[26:29]
	v_mfma_f32_16x16x32_bf16 v[14:17], v[154:157], v[218:221], v[14:17]
	v_mfma_f32_16x16x32_bf16 v[10:13], v[162:165], v[218:221], v[10:13]
	s_setprio 0
	s_setprio 1
	v_mfma_f32_16x16x32_bf16 v[54:57], v[166:169], v[182:185], v[54:57]
	v_mfma_f32_16x16x32_bf16 v[50:53], v[174:177], v[182:185], v[50:53]
	v_mfma_f32_16x16x32_bf16 v[38:41], v[166:169], v[190:193], v[38:41]
	v_mfma_f32_16x16x32_bf16 v[34:37], v[174:177], v[190:193], v[34:37]
	v_mfma_f32_16x16x32_bf16 v[22:25], v[166:169], v[206:209], v[22:25]
	v_mfma_f32_16x16x32_bf16 v[18:21], v[174:177], v[206:209], v[18:21]
	v_mfma_f32_16x16x32_bf16 v[6:9], v[166:169], v[214:217], v[6:9]
	v_mfma_f32_16x16x32_bf16 v[2:5], v[174:177], v[214:217], v[2:5]
	v_mfma_f32_16x16x32_bf16 v[54:57], v[170:173], v[186:189], v[54:57]
	v_mfma_f32_16x16x32_bf16 v[50:53], v[178:181], v[186:189], v[50:53]
	v_mfma_f32_16x16x32_bf16 v[38:41], v[170:173], v[202:205], v[38:41]
	v_mfma_f32_16x16x32_bf16 v[34:37], v[178:181], v[202:205], v[34:37]
	v_mfma_f32_16x16x32_bf16 v[22:25], v[170:173], v[210:213], v[22:25]
	v_mfma_f32_16x16x32_bf16 v[18:21], v[178:181], v[210:213], v[18:21]
	v_mfma_f32_16x16x32_bf16 v[6:9], v[170:173], v[218:221], v[6:9]
	v_mfma_f32_16x16x32_bf16 v[2:5], v[178:181], v[218:221], v[2:5]
	s_setprio 0
	s_barrier
	s_add_i32 s85, 0, 0x18000
	v_add_u32_e32 v0, s85, v152
	s_add_i32 s86, 0, 0x1c000
	ds_read_b128 v[148:151], v0
	ds_read_b128 v[154:157], v0 offset:1024
	ds_read_b128 v[158:161], v0 offset:2048
	ds_read_b128 v[162:165], v0 offset:3072
	v_add_u32_e32 v0, s86, v152
	ds_read_b128 v[166:169], v0
	ds_read_b128 v[170:173], v0 offset:1024
	ds_read_b128 v[174:177], v0 offset:2048
	ds_read_b128 v[178:181], v0 offset:3072
	s_add_u32 s38, s38, 0x40000
	s_addc_u32 s39, s39, 0
	s_mov_b32 m0, s55
	v_lshl_add_u64 v[222:223], s[38:39], 0, v[136:137]
	ds_read_b128 v[182:185], v153 offset:32768
	ds_read_b128 v[186:189], v153 offset:33792
	ds_read_b128 v[190:193], v153 offset:34816
	ds_read_b128 v[202:205], v153 offset:35840
	ds_read_b128 v[206:209], v153 offset:36864
	ds_read_b128 v[210:213], v153 offset:37888
	ds_read_b128 v[214:217], v153 offset:38912
	ds_read_b128 v[218:221], v153 offset:39936
	global_load_lds_dwordx4 v[222:223], off
	v_lshl_add_u64 v[222:223], s[38:39], 0, v[132:133]
	s_mov_b32 m0, s56
	s_nop 0
	global_load_lds_dwordx4 v[222:223], off
	s_waitcnt vmcnt(8)
	s_waitcnt lgkmcnt(0)
	s_barrier
	s_setprio 1
	s_waitcnt lgkmcnt(0)
	v_mfma_f32_16x16x32_bf16 v[126:129], v[148:151], v[182:185], v[126:129]
	v_mfma_f32_16x16x32_bf16 v[122:125], v[158:161], v[182:185], v[122:125]
	v_mfma_f32_16x16x32_bf16 v[110:113], v[148:151], v[190:193], v[110:113]
	v_mfma_f32_16x16x32_bf16 v[106:109], v[158:161], v[190:193], v[106:109]
	v_mfma_f32_16x16x32_bf16 v[94:97], v[148:151], v[206:209], v[94:97]
	v_mfma_f32_16x16x32_bf16 v[90:93], v[158:161], v[206:209], v[90:93]
	v_mfma_f32_16x16x32_bf16 v[78:81], v[148:151], v[214:217], v[78:81]
	v_mfma_f32_16x16x32_bf16 v[74:77], v[158:161], v[214:217], v[74:77]
	v_mfma_f32_16x16x32_bf16 v[126:129], v[154:157], v[186:189], v[126:129]
	v_mfma_f32_16x16x32_bf16 v[122:125], v[162:165], v[186:189], v[122:125]
	v_mfma_f32_16x16x32_bf16 v[110:113], v[154:157], v[202:205], v[110:113]
	v_mfma_f32_16x16x32_bf16 v[106:109], v[162:165], v[202:205], v[106:109]
	v_mfma_f32_16x16x32_bf16 v[94:97], v[154:157], v[210:213], v[94:97]
	v_mfma_f32_16x16x32_bf16 v[90:93], v[162:165], v[210:213], v[90:93]
	v_mfma_f32_16x16x32_bf16 v[78:81], v[154:157], v[218:221], v[78:81]
	v_mfma_f32_16x16x32_bf16 v[74:77], v[162:165], v[218:221], v[74:77]
	s_setprio 0
	s_setprio 1
	v_mfma_f32_16x16x32_bf16 v[118:121], v[166:169], v[182:185], v[118:121]
	v_mfma_f32_16x16x32_bf16 v[114:117], v[174:177], v[182:185], v[114:117]
	v_mfma_f32_16x16x32_bf16 v[102:105], v[166:169], v[190:193], v[102:105]
	v_mfma_f32_16x16x32_bf16 v[98:101], v[174:177], v[190:193], v[98:101]
	v_mfma_f32_16x16x32_bf16 v[86:89], v[166:169], v[206:209], v[86:89]
	v_mfma_f32_16x16x32_bf16 v[82:85], v[174:177], v[206:209], v[82:85]
	v_mfma_f32_16x16x32_bf16 v[70:73], v[166:169], v[214:217], v[70:73]
	v_mfma_f32_16x16x32_bf16 v[66:69], v[174:177], v[214:217], v[66:69]
	v_mfma_f32_16x16x32_bf16 v[118:121], v[170:173], v[186:189], v[118:121]
	v_mfma_f32_16x16x32_bf16 v[114:117], v[178:181], v[186:189], v[114:117]
	v_mfma_f32_16x16x32_bf16 v[102:105], v[170:173], v[202:205], v[102:105]
	v_mfma_f32_16x16x32_bf16 v[98:101], v[178:181], v[202:205], v[98:101]
	v_mfma_f32_16x16x32_bf16 v[86:89], v[170:173], v[210:213], v[86:89]
	v_mfma_f32_16x16x32_bf16 v[82:85], v[178:181], v[210:213], v[82:85]
	v_mfma_f32_16x16x32_bf16 v[70:73], v[170:173], v[218:221], v[70:73]
	v_mfma_f32_16x16x32_bf16 v[66:69], v[178:181], v[218:221], v[66:69]
	s_setprio 0
	s_barrier
	s_add_i32 s38, s85, s44
	v_lshl_add_u64 v[194:195], v[194:195], 0, s[90:91]
	s_mov_b32 m0, s38
	ds_read_b128 v[182:185], v153 offset:49152
	ds_read_b128 v[186:189], v153 offset:50176
	ds_read_b128 v[190:193], v153 offset:51200
	ds_read_b128 v[202:205], v153 offset:52224
	ds_read_b128 v[206:209], v153 offset:53248
	ds_read_b128 v[210:213], v153 offset:54272
	ds_read_b128 v[214:217], v153 offset:55296
	ds_read_b128 v[218:221], v153 offset:56320
	global_load_lds_dwordx4 v[194:195], off
	s_add_i32 m0, s38, 0x2000
	s_add_u32 s36, s36, 0x40080
	v_lshl_add_u64 v[194:195], v[198:199], 0, s[90:91]
	s_addc_u32 s37, s37, 0
	s_add_i32 s38, s86, s44
	global_load_lds_dwordx4 v[194:195], off
	v_lshl_add_u64 v[194:195], s[36:37], 0, v[134:135]
	s_mov_b32 m0, s38
	s_nop 0
	global_load_lds_dwordx4 v[194:195], off
	v_lshl_add_u64 v[194:195], s[36:37], 0, v[130:131]
	s_add_i32 m0, s38, 0x2000
	s_nop 0
	global_load_lds_dwordx4 v[194:195], off
	v_lshl_add_u64 v[194:195], s[34:35], 0, v[136:137]
	s_mov_b32 m0, s58
	s_nop 0
	global_load_lds_dwordx4 v[194:195], off
	v_lshl_add_u64 v[194:195], s[34:35], 0, v[132:133]
	s_mov_b32 m0, s59
	s_nop 0
	global_load_lds_dwordx4 v[194:195], off
	s_waitcnt vmcnt(8)
	s_waitcnt lgkmcnt(0)
	s_barrier
	s_setprio 1
	s_waitcnt lgkmcnt(0)
	v_mfma_f32_16x16x32_bf16 v[62:65], v[148:151], v[182:185], v[62:65]
	v_mfma_f32_16x16x32_bf16 v[58:61], v[158:161], v[182:185], v[58:61]
	v_mfma_f32_16x16x32_bf16 v[46:49], v[148:151], v[190:193], v[46:49]
	v_mfma_f32_16x16x32_bf16 v[42:45], v[158:161], v[190:193], v[42:45]
	v_mfma_f32_16x16x32_bf16 v[30:33], v[148:151], v[206:209], v[30:33]
	v_mfma_f32_16x16x32_bf16 v[26:29], v[158:161], v[206:209], v[26:29]
	v_mfma_f32_16x16x32_bf16 v[14:17], v[148:151], v[214:217], v[14:17]
	v_mfma_f32_16x16x32_bf16 v[10:13], v[158:161], v[214:217], v[10:13]
	v_mfma_f32_16x16x32_bf16 v[62:65], v[154:157], v[186:189], v[62:65]
	v_mfma_f32_16x16x32_bf16 v[58:61], v[162:165], v[186:189], v[58:61]
	v_mfma_f32_16x16x32_bf16 v[46:49], v[154:157], v[202:205], v[46:49]
	v_mfma_f32_16x16x32_bf16 v[42:45], v[162:165], v[202:205], v[42:45]
	v_mfma_f32_16x16x32_bf16 v[30:33], v[154:157], v[210:213], v[30:33]
	v_mfma_f32_16x16x32_bf16 v[26:29], v[162:165], v[210:213], v[26:29]
	v_mfma_f32_16x16x32_bf16 v[14:17], v[154:157], v[218:221], v[14:17]
	v_mfma_f32_16x16x32_bf16 v[10:13], v[162:165], v[218:221], v[10:13]
	s_setprio 0
	s_setprio 1
	v_mfma_f32_16x16x32_bf16 v[54:57], v[166:169], v[182:185], v[54:57]
	v_mfma_f32_16x16x32_bf16 v[50:53], v[174:177], v[182:185], v[50:53]
	v_mfma_f32_16x16x32_bf16 v[38:41], v[166:169], v[190:193], v[38:41]
	v_mfma_f32_16x16x32_bf16 v[34:37], v[174:177], v[190:193], v[34:37]
	v_mfma_f32_16x16x32_bf16 v[22:25], v[166:169], v[206:209], v[22:25]
	v_mfma_f32_16x16x32_bf16 v[18:21], v[174:177], v[206:209], v[18:21]
	v_mfma_f32_16x16x32_bf16 v[6:9], v[166:169], v[214:217], v[6:9]
	v_mfma_f32_16x16x32_bf16 v[2:5], v[174:177], v[214:217], v[2:5]
	v_mfma_f32_16x16x32_bf16 v[54:57], v[170:173], v[186:189], v[54:57]
	v_mfma_f32_16x16x32_bf16 v[50:53], v[178:181], v[186:189], v[50:53]
	v_mfma_f32_16x16x32_bf16 v[38:41], v[170:173], v[202:205], v[38:41]
	v_mfma_f32_16x16x32_bf16 v[34:37], v[178:181], v[202:205], v[34:37]
	v_mfma_f32_16x16x32_bf16 v[22:25], v[170:173], v[210:213], v[22:25]
	v_mfma_f32_16x16x32_bf16 v[18:21], v[178:181], v[210:213], v[18:21]
	v_mfma_f32_16x16x32_bf16 v[6:9], v[170:173], v[218:221], v[6:9]
	v_mfma_f32_16x16x32_bf16 v[2:5], v[178:181], v[218:221], v[2:5]
	s_setprio 0
	s_add_i32 s78, s78, 2
	s_add_u32 s30, s30, 0x100
	s_addc_u32 s31, s31, 0
	s_add_u32 s34, s28, s30
	s_addc_u32 s35, s29, s31
	s_add_u32 s38, s34, 0x100
	s_addc_u32 s39, s35, 0
	s_add_u32 s36, s75, s30
	s_addc_u32 s37, s76, s31
	s_add_u32 s34, s34, 0x180
	s_addc_u32 s35, s35, 0
	s_add_i32 s85, 0, 0x10000
	s_add_i32 vcc_lo, 0, 0x14000
	s_cmp_gt_u32 s78, 13
	s_barrier
	s_cbranch_scc0 .Lkvk_body
	s_and_b64 vcc, exec, s[16:17]
	s_cbranch_vccz .LBB0_348
	s_barrier

.Lg3k_body:
	v_add_u32_e32 v0, s87, v148
	ds_read_b128 v[150:153], v0
	ds_read_b128 v[154:157], v0 offset:1024
	ds_read_b128 v[158:161], v0 offset:2048
	ds_read_b128 v[162:165], v0 offset:3072
	v_add_u32_e32 v0, s65, v148
	ds_read_b128 v[166:169], v0
	ds_read_b128 v[170:173], v0 offset:1024
	ds_read_b128 v[174:177], v0 offset:2048
	ds_read_b128 v[178:181], v0 offset:3072
	s_cmpk_eq_i32 s34, 0x700
	s_cselect_b32 s37, s76, s5
	s_cselect_b32 s36, s75, s4
	s_cselect_b32 s39, s23, s39
	s_cselect_b32 s38, s74, s38
	s_cselect_b32 s41, s25, s41
	s_cselect_b32 s40, s73, s40
	v_lshl_add_u64 v[194:195], v[144:145], 0, s[34:35]
	s_add_i32 m0, s55, 0xc000
	ds_read_b128 v[182:185], v149
	ds_read_b128 v[186:189], v149 offset:1024
	ds_read_b128 v[190:193], v149 offset:2048
	ds_read_b128 v[202:205], v149 offset:3072
	ds_read_b128 v[206:209], v149 offset:4096
	ds_read_b128 v[210:213], v149 offset:5120
	ds_read_b128 v[214:217], v149 offset:6144
	ds_read_b128 v[218:221], v149 offset:7168
	global_load_lds_dwordx4 v[194:195], off
	v_lshl_add_u64 v[194:195], v[146:147], 0, s[34:35]
	s_add_i32 m0, s55, 0xe000
	s_nop 0
	global_load_lds_dwordx4 v[194:195], off
	s_waitcnt vmcnt(8)
	s_waitcnt lgkmcnt(0)
	s_barrier
	s_setprio 1
	s_waitcnt lgkmcnt(0)
	v_mfma_f32_16x16x32_bf16 v[126:129], v[150:153], v[182:185], v[126:129]
	v_mfma_f32_16x16x32_bf16 v[122:125], v[158:161], v[182:185], v[122:125]
	v_mfma_f32_16x16x32_bf16 v[110:113], v[150:153], v[190:193], v[110:113]
	v_mfma_f32_16x16x32_bf16 v[106:109], v[158:161], v[190:193], v[106:109]
	v_mfma_f32_16x16x32_bf16 v[94:97], v[150:153], v[206:209], v[94:97]
	v_mfma_f32_16x16x32_bf16 v[90:93], v[158:161], v[206:209], v[90:93]
	v_mfma_f32_16x16x32_bf16 v[78:81], v[150:153], v[214:217], v[78:81]
	v_mfma_f32_16x16x32_bf16 v[74:77], v[158:161], v[214:217], v[74:77]
	v_mfma_f32_16x16x32_bf16 v[126:129], v[154:157], v[186:189], v[126:129]
	v_mfma_f32_16x16x32_bf16 v[122:125], v[162:165], v[186:189], v[122:125]
	v_mfma_f32_16x16x32_bf16 v[110:113], v[154:157], v[202:205], v[110:113]
	v_mfma_f32_16x16x32_bf16 v[106:109], v[162:165], v[202:205], v[106:109]
	v_mfma_f32_16x16x32_bf16 v[94:97], v[154:157], v[210:213], v[94:97]
	v_mfma_f32_16x16x32_bf16 v[90:93], v[162:165], v[210:213], v[90:93]
	v_mfma_f32_16x16x32_bf16 v[78:81], v[154:157], v[218:221], v[78:81]
	v_mfma_f32_16x16x32_bf16 v[74:77], v[162:165], v[218:221], v[74:77]
	s_setprio 0
	s_setprio 1
	v_mfma_f32_16x16x32_bf16 v[118:121], v[166:169], v[182:185], v[118:121]
	v_mfma_f32_16x16x32_bf16 v[114:117], v[174:177], v[182:185], v[114:117]
	v_mfma_f32_16x16x32_bf16 v[102:105], v[166:169], v[190:193], v[102:105]
	v_mfma_f32_16x16x32_bf16 v[98:101], v[174:177], v[190:193], v[98:101]
	v_mfma_f32_16x16x32_bf16 v[86:89], v[166:169], v[206:209], v[86:89]
	v_mfma_f32_16x16x32_bf16 v[82:85], v[174:177], v[206:209], v[82:85]
	v_mfma_f32_16x16x32_bf16 v[70:73], v[166:169], v[214:217], v[70:73]
	v_mfma_f32_16x16x32_bf16 v[66:69], v[174:177], v[214:217], v[66:69]
	v_mfma_f32_16x16x32_bf16 v[118:121], v[170:173], v[186:189], v[118:121]
	v_mfma_f32_16x16x32_bf16 v[114:117], v[178:181], v[186:189], v[114:117]
	v_mfma_f32_16x16x32_bf16 v[102:105], v[170:173], v[202:205], v[102:105]
	v_mfma_f32_16x16x32_bf16 v[98:101], v[178:181], v[202:205], v[98:101]
	v_mfma_f32_16x16x32_bf16 v[86:89], v[170:173], v[210:213], v[86:89]
	v_mfma_f32_16x16x32_bf16 v[82:85], v[178:181], v[210:213], v[82:85]
	v_mfma_f32_16x16x32_bf16 v[70:73], v[170:173], v[218:221], v[70:73]
	v_mfma_f32_16x16x32_bf16 v[66:69], v[178:181], v[218:221], v[66:69]
	s_setprio 0
	s_barrier
	s_add_i32 s4, s87, s51
	v_lshl_add_u64 v[194:195], s[38:39], 0, v[134:135]
	s_mov_b32 m0, s4
	ds_read_b128 v[182:185], v149 offset:16384
	ds_read_b128 v[186:189], v149 offset:17408
	ds_read_b128 v[190:193], v149 offset:18432
	ds_read_b128 v[202:205], v149 offset:19456
	ds_read_b128 v[206:209], v149 offset:20480
	ds_read_b128 v[210:213], v149 offset:21504
	ds_read_b128 v[214:217], v149 offset:22528
	ds_read_b128 v[218:221], v149 offset:23552
	global_load_lds_dwordx4 v[194:195], off
	s_add_i32 m0, s4, 0x2000
	s_add_u32 vcc_lo, s38, 0x40000
	v_lshl_add_u64 v[198:199], s[38:39], 0, v[130:131]
	s_addc_u32 vcc_hi, s39, 0
	s_add_i32 s4, s65, s51
	global_load_lds_dwordx4 v[198:199], off
	v_lshl_add_u64 v[222:223], vcc, 0, v[134:135]
	s_mov_b32 m0, s4
	s_nop 0
	global_load_lds_dwordx4 v[222:223], off
	v_lshl_add_u64 v[222:223], vcc, 0, v[130:131]
	s_add_i32 m0, s4, 0x2000
	s_nop 0
	global_load_lds_dwordx4 v[222:223], off
	v_lshl_add_u64 v[222:223], s[40:41], 0, v[136:137]
	s_mov_b32 m0, s55
	s_nop 0
	global_load_lds_dwordx4 v[222:223], off
	v_lshl_add_u64 v[222:223], s[40:41], 0, v[132:133]
	s_mov_b32 m0, s56
	s_nop 0
	global_load_lds_dwordx4 v[222:223], off
	s_waitcnt vmcnt(8)
	s_waitcnt lgkmcnt(0)
	s_barrier
	s_setprio 1
	s_waitcnt lgkmcnt(0)
	v_mfma_f32_16x16x32_bf16 v[62:65], v[150:153], v[182:185], v[62:65]
	v_mfma_f32_16x16x32_bf16 v[58:61], v[158:161], v[182:185], v[58:61]
	v_mfma_f32_16x16x32_bf16 v[46:49], v[150:153], v[190:193], v[46:49]
	v_mfma_f32_16x16x32_bf16 v[42:45], v[158:161], v[190:193], v[42:45]
	v_mfma_f32_16x16x32_bf16 v[30:33], v[150:153], v[206:209], v[30:33]
	v_mfma_f32_16x16x32_bf16 v[26:29], v[158:161], v[206:209], v[26:29]
	v_mfma_f32_16x16x32_bf16 v[14:17], v[150:153], v[214:217], v[14:17]
	v_mfma_f32_16x16x32_bf16 v[10:13], v[158:161], v[214:217], v[10:13]
	v_mfma_f32_16x16x32_bf16 v[62:65], v[154:157], v[186:189], v[62:65]
	v_mfma_f32_16x16x32_bf16 v[58:61], v[162:165], v[186:189], v[58:61]
	v_mfma_f32_16x16x32_bf16 v[46:49], v[154:157], v[202:205], v[46:49]
	v_mfma_f32_16x16x32_bf16 v[42:45], v[162:165], v[202:205], v[42:45]
	v_mfma_f32_16x16x32_bf16 v[30:33], v[154:157], v[210:213], v[30:33]
	v_mfma_f32_16x16x32_bf16 v[26:29], v[162:165], v[210:213], v[26:29]
	v_mfma_f32_16x16x32_bf16 v[14:17], v[154:157], v[218:221], v[14:17]
	v_mfma_f32_16x16x32_bf16 v[10:13], v[162:165], v[218:221], v[10:13]
	s_setprio 0
	s_setprio 1
	v_mfma_f32_16x16x32_bf16 v[54:57], v[166:169], v[182:185], v[54:57]
	v_mfma_f32_16x16x32_bf16 v[50:53], v[174:177], v[182:185], v[50:53]
	v_mfma_f32_16x16x32_bf16 v[38:41], v[166:169], v[190:193], v[38:41]
	v_mfma_f32_16x16x32_bf16 v[34:37], v[174:177], v[190:193], v[34:37]
	v_mfma_f32_16x16x32_bf16 v[22:25], v[166:169], v[206:209], v[22:25]
	v_mfma_f32_16x16x32_bf16 v[18:21], v[174:177], v[206:209], v[18:21]
	v_mfma_f32_16x16x32_bf16 v[6:9], v[166:169], v[214:217], v[6:9]
	v_mfma_f32_16x16x32_bf16 v[2:5], v[174:177], v[214:217], v[2:5]
	v_mfma_f32_16x16x32_bf16 v[54:57], v[170:173], v[186:189], v[54:57]
	v_mfma_f32_16x16x32_bf16 v[50:53], v[178:181], v[186:189], v[50:53]
	v_mfma_f32_16x16x32_bf16 v[38:41], v[170:173], v[202:205], v[38:41]
	v_mfma_f32_16x16x32_bf16 v[34:37], v[178:181], v[202:205], v[34:37]
	v_mfma_f32_16x16x32_bf16 v[22:25], v[170:173], v[210:213], v[22:25]
	v_mfma_f32_16x16x32_bf16 v[18:21], v[178:181], v[210:213], v[18:21]
	v_mfma_f32_16x16x32_bf16 v[6:9], v[170:173], v[218:221], v[6:9]
	v_mfma_f32_16x16x32_bf16 v[2:5], v[178:181], v[218:221], v[2:5]
	s_setprio 0
	s_barrier
	s_add_i32 s4, 0, 0x18000
	v_add_u32_e32 v0, s4, v148
	s_add_i32 s5, 0, 0x1c000
	ds_read_b128 v[150:153], v0
	ds_read_b128 v[154:157], v0 offset:1024
	ds_read_b128 v[158:161], v0 offset:2048
	ds_read_b128 v[162:165], v0 offset:3072
	v_add_u32_e32 v0, s5, v148
	ds_read_b128 v[166:169], v0
	ds_read_b128 v[170:173], v0 offset:1024
	ds_read_b128 v[174:177], v0 offset:2048
	ds_read_b128 v[178:181], v0 offset:3072
	s_add_u32 s40, s40, 0x40000
	s_addc_u32 s41, s41, 0
	s_mov_b32 m0, s57
	v_lshl_add_u64 v[222:223], s[40:41], 0, v[136:137]
	ds_read_b128 v[182:185], v149 offset:32768
	ds_read_b128 v[186:189], v149 offset:33792
	ds_read_b128 v[190:193], v149 offset:34816
	ds_read_b128 v[202:205], v149 offset:35840
	ds_read_b128 v[206:209], v149 offset:36864
	ds_read_b128 v[210:213], v149 offset:37888
	ds_read_b128 v[214:217], v149 offset:38912
	ds_read_b128 v[218:221], v149 offset:39936
	global_load_lds_dwordx4 v[222:223], off
	v_lshl_add_u64 v[222:223], s[40:41], 0, v[132:133]
	s_mov_b32 m0, s58
	s_nop 0
	global_load_lds_dwordx4 v[222:223], off
	s_waitcnt vmcnt(8)
	s_waitcnt lgkmcnt(0)
	s_barrier
	s_setprio 1
	s_waitcnt lgkmcnt(0)
	v_mfma_f32_16x16x32_bf16 v[126:129], v[150:153], v[182:185], v[126:129]
	v_mfma_f32_16x16x32_bf16 v[122:125], v[158:161], v[182:185], v[122:125]
	v_mfma_f32_16x16x32_bf16 v[110:113], v[150:153], v[190:193], v[110:113]
	v_mfma_f32_16x16x32_bf16 v[106:109], v[158:161], v[190:193], v[106:109]
	v_mfma_f32_16x16x32_bf16 v[94:97], v[150:153], v[206:209], v[94:97]
	v_mfma_f32_16x16x32_bf16 v[90:93], v[158:161], v[206:209], v[90:93]
	v_mfma_f32_16x16x32_bf16 v[78:81], v[150:153], v[214:217], v[78:81]
	v_mfma_f32_16x16x32_bf16 v[74:77], v[158:161], v[214:217], v[74:77]
	v_mfma_f32_16x16x32_bf16 v[126:129], v[154:157], v[186:189], v[126:129]
	v_mfma_f32_16x16x32_bf16 v[122:125], v[162:165], v[186:189], v[122:125]
	v_mfma_f32_16x16x32_bf16 v[110:113], v[154:157], v[202:205], v[110:113]
	v_mfma_f32_16x16x32_bf16 v[106:109], v[162:165], v[202:205], v[106:109]
	v_mfma_f32_16x16x32_bf16 v[94:97], v[154:157], v[210:213], v[94:97]
	v_mfma_f32_16x16x32_bf16 v[90:93], v[162:165], v[210:213], v[90:93]
	v_mfma_f32_16x16x32_bf16 v[78:81], v[154:157], v[218:221], v[78:81]
	v_mfma_f32_16x16x32_bf16 v[74:77], v[162:165], v[218:221], v[74:77]
	s_setprio 0
	s_setprio 1
	v_mfma_f32_16x16x32_bf16 v[118:121], v[166:169], v[182:185], v[118:121]
	v_mfma_f32_16x16x32_bf16 v[114:117], v[174:177], v[182:185], v[114:117]
	v_mfma_f32_16x16x32_bf16 v[102:105], v[166:169], v[190:193], v[102:105]
	v_mfma_f32_16x16x32_bf16 v[98:101], v[174:177], v[190:193], v[98:101]
	v_mfma_f32_16x16x32_bf16 v[86:89], v[166:169], v[206:209], v[86:89]
	v_mfma_f32_16x16x32_bf16 v[82:85], v[174:177], v[206:209], v[82:85]
	v_mfma_f32_16x16x32_bf16 v[70:73], v[166:169], v[214:217], v[70:73]
	v_mfma_f32_16x16x32_bf16 v[66:69], v[174:177], v[214:217], v[66:69]
	v_mfma_f32_16x16x32_bf16 v[118:121], v[170:173], v[186:189], v[118:121]
	v_mfma_f32_16x16x32_bf16 v[114:117], v[178:181], v[186:189], v[114:117]
	v_mfma_f32_16x16x32_bf16 v[102:105], v[170:173], v[202:205], v[102:105]
	v_mfma_f32_16x16x32_bf16 v[98:101], v[178:181], v[202:205], v[98:101]
	v_mfma_f32_16x16x32_bf16 v[86:89], v[170:173], v[210:213], v[86:89]
	v_mfma_f32_16x16x32_bf16 v[82:85], v[178:181], v[210:213], v[82:85]
	v_mfma_f32_16x16x32_bf16 v[70:73], v[170:173], v[218:221], v[70:73]
	v_mfma_f32_16x16x32_bf16 v[66:69], v[178:181], v[218:221], v[66:69]
	s_setprio 0
	s_barrier
	s_add_i32 s4, s4, s51
	v_lshl_add_u64 v[194:195], v[194:195], 0, s[90:91]
	s_mov_b32 m0, s4
	ds_read_b128 v[182:185], v149 offset:49152
	ds_read_b128 v[186:189], v149 offset:50176
	ds_read_b128 v[190:193], v149 offset:51200
	ds_read_b128 v[202:205], v149 offset:52224
	ds_read_b128 v[206:209], v149 offset:53248
	ds_read_b128 v[210:213], v149 offset:54272
	ds_read_b128 v[214:217], v149 offset:55296
	ds_read_b128 v[218:221], v149 offset:56320
	global_load_lds_dwordx4 v[194:195], off
	s_add_i32 m0, s4, 0x2000
	s_add_u32 s38, s38, 0x40080
	v_lshl_add_u64 v[194:195], v[198:199], 0, s[90:91]
	s_addc_u32 s39, s39, 0
	s_add_i32 s4, s5, s51
	global_load_lds_dwordx4 v[194:195], off
	v_lshl_add_u64 v[194:195], s[38:39], 0, v[134:135]
	s_mov_b32 m0, s4
	s_nop 0
	global_load_lds_dwordx4 v[194:195], off
	v_lshl_add_u64 v[194:195], s[38:39], 0, v[130:131]
	s_add_i32 m0, s4, 0x2000
	s_nop 0
	global_load_lds_dwordx4 v[194:195], off
	v_lshl_add_u64 v[194:195], s[36:37], 0, v[136:137]
	s_mov_b32 m0, s68
	s_nop 0
	global_load_lds_dwordx4 v[194:195], off
	v_lshl_add_u64 v[194:195], s[36:37], 0, v[132:133]
	s_mov_b32 m0, s69
	s_nop 0
	global_load_lds_dwordx4 v[194:195], off
	s_waitcnt vmcnt(8)
	s_waitcnt lgkmcnt(0)
	s_barrier
	s_setprio 1
	s_waitcnt lgkmcnt(0)
	v_mfma_f32_16x16x32_bf16 v[62:65], v[150:153], v[182:185], v[62:65]
	v_mfma_f32_16x16x32_bf16 v[58:61], v[158:161], v[182:185], v[58:61]
	v_mfma_f32_16x16x32_bf16 v[46:49], v[150:153], v[190:193], v[46:49]
	v_mfma_f32_16x16x32_bf16 v[42:45], v[158:161], v[190:193], v[42:45]
	v_mfma_f32_16x16x32_bf16 v[30:33], v[150:153], v[206:209], v[30:33]
	v_mfma_f32_16x16x32_bf16 v[26:29], v[158:161], v[206:209], v[26:29]
	v_mfma_f32_16x16x32_bf16 v[14:17], v[150:153], v[214:217], v[14:17]
	v_mfma_f32_16x16x32_bf16 v[10:13], v[158:161], v[214:217], v[10:13]
	v_mfma_f32_16x16x32_bf16 v[62:65], v[154:157], v[186:189], v[62:65]
	v_mfma_f32_16x16x32_bf16 v[58:61], v[162:165], v[186:189], v[58:61]
	v_mfma_f32_16x16x32_bf16 v[46:49], v[154:157], v[202:205], v[46:49]
	v_mfma_f32_16x16x32_bf16 v[42:45], v[162:165], v[202:205], v[42:45]
	v_mfma_f32_16x16x32_bf16 v[30:33], v[154:157], v[210:213], v[30:33]
	v_mfma_f32_16x16x32_bf16 v[26:29], v[162:165], v[210:213], v[26:29]
	v_mfma_f32_16x16x32_bf16 v[14:17], v[154:157], v[218:221], v[14:17]
	v_mfma_f32_16x16x32_bf16 v[10:13], v[162:165], v[218:221], v[10:13]
	s_setprio 0
	s_setprio 1
	v_mfma_f32_16x16x32_bf16 v[54:57], v[166:169], v[182:185], v[54:57]
	v_mfma_f32_16x16x32_bf16 v[50:53], v[174:177], v[182:185], v[50:53]
	v_mfma_f32_16x16x32_bf16 v[38:41], v[166:169], v[190:193], v[38:41]
	v_mfma_f32_16x16x32_bf16 v[34:37], v[174:177], v[190:193], v[34:37]
	v_mfma_f32_16x16x32_bf16 v[22:25], v[166:169], v[206:209], v[22:25]
	v_mfma_f32_16x16x32_bf16 v[18:21], v[174:177], v[206:209], v[18:21]
	v_mfma_f32_16x16x32_bf16 v[6:9], v[166:169], v[214:217], v[6:9]
	v_mfma_f32_16x16x32_bf16 v[2:5], v[174:177], v[214:217], v[2:5]
	v_mfma_f32_16x16x32_bf16 v[54:57], v[170:173], v[186:189], v[54:57]
	v_mfma_f32_16x16x32_bf16 v[50:53], v[178:181], v[186:189], v[50:53]
	v_mfma_f32_16x16x32_bf16 v[38:41], v[170:173], v[202:205], v[38:41]
	v_mfma_f32_16x16x32_bf16 v[34:37], v[178:181], v[202:205], v[34:37]
	v_mfma_f32_16x16x32_bf16 v[22:25], v[170:173], v[210:213], v[22:25]
	v_mfma_f32_16x16x32_bf16 v[18:21], v[178:181], v[210:213], v[18:21]
	v_mfma_f32_16x16x32_bf16 v[6:9], v[170:173], v[218:221], v[6:9]
	v_mfma_f32_16x16x32_bf16 v[2:5], v[178:181], v[218:221], v[2:5]
	s_setprio 0
	s_add_i32 s86, s86, 2
	s_add_u32 s34, s34, 0x100
	s_addc_u32 s35, s35, 0
	s_add_u32 s4, s30, s34
	s_addc_u32 s5, s31, s35
	s_add_u32 s40, s4, 0x100
	s_addc_u32 s41, s5, 0
	s_add_u32 s38, s78, s34
	s_addc_u32 s39, s85, s35
	s_add_u32 s4, s4, 0x180
	s_addc_u32 s5, s5, 0
	s_add_i32 s87, 0, 0x10000
	s_add_i32 s65, 0, 0x14000
	s_cmp_gt_u32 s86, 13
	s_barrier
	s_cbranch_scc0 .Lg3k_body
	s_and_b64 vcc, exec, s[20:21]
	s_cbranch_vccz .LBB0_678
	s_barrier

.Lg4k_body:
	v_add_u32_e32 v138, s65, v231
	v_add_u32_e32 v162, s87, v231
	ds_read_b128 v[126:129], v138
	ds_read_b128 v[130:133], v138 offset:1024
	ds_read_b128 v[134:137], v138 offset:2048
	ds_read_b128 v[138:141], v138 offset:3072
	ds_read_b128 v[142:145], v162
	ds_read_b128 v[146:149], v162 offset:1024
	ds_read_b128 v[158:161], v162 offset:2048
	ds_read_b128 v[162:165], v162 offset:3072
	s_cmpk_eq_i32 s34, 0x700
	s_cselect_b32 s37, s76, s5
	s_cselect_b32 s36, s75, s4
	s_cselect_b32 s39, s23, s39
	s_cselect_b32 s38, s74, s38
	s_cselect_b32 s41, s25, s41
	s_cselect_b32 s40, s73, s40
	v_lshl_add_u64 v[194:195], v[118:119], 0, s[34:35]
	s_add_i32 m0, s56, 0xc000
	ds_read_b128 v[166:169], v242
	ds_read_b128 v[170:173], v242 offset:1024
	ds_read_b128 v[174:177], v242 offset:2048
	ds_read_b128 v[178:181], v242 offset:3072
	ds_read_b128 v[182:185], v242 offset:4096
	ds_read_b128 v[186:189], v242 offset:5120
	ds_read_b128 v[208:211], v242 offset:6144
	ds_read_b128 v[212:215], v242 offset:7168
	global_load_lds_dwordx4 v[194:195], off
	v_lshl_add_u64 v[194:195], v[120:121], 0, s[34:35]
	s_add_i32 m0, s56, 0xe000
	s_nop 0
	global_load_lds_dwordx4 v[194:195], off
	s_waitcnt vmcnt(8)
	s_waitcnt lgkmcnt(0)
	s_barrier
	s_setprio 1
	s_waitcnt lgkmcnt(0)
	v_mfma_f32_16x16x32_bf16 v[154:157], v[126:129], v[166:169], v[154:157]
	v_mfma_f32_16x16x32_bf16 v[150:153], v[134:137], v[166:169], v[150:153]
	v_mfma_f32_16x16x32_bf16 v[110:113], v[126:129], v[174:177], v[110:113]
	v_mfma_f32_16x16x32_bf16 v[106:109], v[134:137], v[174:177], v[106:109]
	v_mfma_f32_16x16x32_bf16 v[94:97], v[126:129], v[182:185], v[94:97]
	v_mfma_f32_16x16x32_bf16 v[90:93], v[134:137], v[182:185], v[90:93]
	v_mfma_f32_16x16x32_bf16 v[78:81], v[126:129], v[208:211], v[78:81]
	v_mfma_f32_16x16x32_bf16 v[74:77], v[134:137], v[208:211], v[74:77]
	v_mfma_f32_16x16x32_bf16 v[154:157], v[130:133], v[170:173], v[154:157]
	v_mfma_f32_16x16x32_bf16 v[150:153], v[138:141], v[170:173], v[150:153]
	v_mfma_f32_16x16x32_bf16 v[110:113], v[130:133], v[178:181], v[110:113]
	v_mfma_f32_16x16x32_bf16 v[106:109], v[138:141], v[178:181], v[106:109]
	v_mfma_f32_16x16x32_bf16 v[94:97], v[130:133], v[186:189], v[94:97]
	v_mfma_f32_16x16x32_bf16 v[90:93], v[138:141], v[186:189], v[90:93]
	v_mfma_f32_16x16x32_bf16 v[78:81], v[130:133], v[212:215], v[78:81]
	v_mfma_f32_16x16x32_bf16 v[74:77], v[138:141], v[212:215], v[74:77]
	s_setprio 0
	s_setprio 1
	v_mfma_f32_16x16x32_bf16 v[122:125], v[142:145], v[166:169], v[122:125]
	v_mfma_f32_16x16x32_bf16 v[114:117], v[158:161], v[166:169], v[114:117]
	v_mfma_f32_16x16x32_bf16 v[102:105], v[142:145], v[174:177], v[102:105]
	v_mfma_f32_16x16x32_bf16 v[98:101], v[158:161], v[174:177], v[98:101]
	v_mfma_f32_16x16x32_bf16 v[86:89], v[142:145], v[182:185], v[86:89]
	v_mfma_f32_16x16x32_bf16 v[82:85], v[158:161], v[182:185], v[82:85]
	v_mfma_f32_16x16x32_bf16 v[70:73], v[142:145], v[208:211], v[70:73]
	v_mfma_f32_16x16x32_bf16 v[66:69], v[158:161], v[208:211], v[66:69]
	v_mfma_f32_16x16x32_bf16 v[122:125], v[146:149], v[170:173], v[122:125]
	v_mfma_f32_16x16x32_bf16 v[114:117], v[162:165], v[170:173], v[114:117]
	v_mfma_f32_16x16x32_bf16 v[102:105], v[146:149], v[178:181], v[102:105]
	v_mfma_f32_16x16x32_bf16 v[98:101], v[162:165], v[178:181], v[98:101]
	v_mfma_f32_16x16x32_bf16 v[86:89], v[146:149], v[186:189], v[86:89]
	v_mfma_f32_16x16x32_bf16 v[82:85], v[162:165], v[186:189], v[82:85]
	v_mfma_f32_16x16x32_bf16 v[70:73], v[146:149], v[212:215], v[70:73]
	v_mfma_f32_16x16x32_bf16 v[66:69], v[162:165], v[212:215], v[66:69]
	s_setprio 0
	s_barrier
	s_add_i32 s4, s65, s51
	v_lshl_add_u64 v[194:195], s[38:39], 0, v[0:1]
	s_mov_b32 m0, s4
	ds_read_b128 v[166:169], v242 offset:16384
	ds_read_b128 v[170:173], v242 offset:17408
	ds_read_b128 v[174:177], v242 offset:18432
	ds_read_b128 v[178:181], v242 offset:19456
	ds_read_b128 v[182:185], v242 offset:20480
	ds_read_b128 v[186:189], v242 offset:21504
	ds_read_b128 v[208:211], v242 offset:22528
	ds_read_b128 v[212:215], v242 offset:23552
	global_load_lds_dwordx4 v[194:195], off
	s_add_i32 m0, s4, 0x2000
	s_add_u32 vcc_lo, s38, 0x40000
	v_lshl_add_u64 v[198:199], s[38:39], 0, v[190:191]
	s_addc_u32 vcc_hi, s39, 0
	s_add_i32 s4, s87, s51
	global_load_lds_dwordx4 v[198:199], off
	v_lshl_add_u64 v[216:217], vcc, 0, v[0:1]
	s_mov_b32 m0, s4
	s_nop 0
	global_load_lds_dwordx4 v[216:217], off
	v_lshl_add_u64 v[216:217], vcc, 0, v[190:191]
	s_add_i32 m0, s4, 0x2000
	s_nop 0
	global_load_lds_dwordx4 v[216:217], off
	v_lshl_add_u64 v[216:217], s[40:41], 0, v[202:203]
	s_mov_b32 m0, s56
	s_nop 0
	global_load_lds_dwordx4 v[216:217], off
	v_lshl_add_u64 v[216:217], s[40:41], 0, v[192:193]
	s_mov_b32 m0, s57
	s_nop 0
	global_load_lds_dwordx4 v[216:217], off
	s_waitcnt vmcnt(8)
	s_waitcnt lgkmcnt(0)
	s_barrier
	s_setprio 1
	s_waitcnt lgkmcnt(0)
	v_mfma_f32_16x16x32_bf16 v[62:65], v[126:129], v[166:169], v[62:65]
	v_mfma_f32_16x16x32_bf16 v[58:61], v[134:137], v[166:169], v[58:61]
	v_mfma_f32_16x16x32_bf16 v[46:49], v[126:129], v[174:177], v[46:49]
	v_mfma_f32_16x16x32_bf16 v[42:45], v[134:137], v[174:177], v[42:45]
	v_mfma_f32_16x16x32_bf16 v[30:33], v[126:129], v[182:185], v[30:33]
	v_mfma_f32_16x16x32_bf16 v[26:29], v[134:137], v[182:185], v[26:29]
	v_mfma_f32_16x16x32_bf16 v[14:17], v[126:129], v[208:211], v[14:17]
	v_mfma_f32_16x16x32_bf16 v[10:13], v[134:137], v[208:211], v[10:13]
	v_mfma_f32_16x16x32_bf16 v[62:65], v[130:133], v[170:173], v[62:65]
	v_mfma_f32_16x16x32_bf16 v[58:61], v[138:141], v[170:173], v[58:61]
	v_mfma_f32_16x16x32_bf16 v[46:49], v[130:133], v[178:181], v[46:49]
	v_mfma_f32_16x16x32_bf16 v[42:45], v[138:141], v[178:181], v[42:45]
	v_mfma_f32_16x16x32_bf16 v[30:33], v[130:133], v[186:189], v[30:33]
	v_mfma_f32_16x16x32_bf16 v[26:29], v[138:141], v[186:189], v[26:29]
	v_mfma_f32_16x16x32_bf16 v[14:17], v[130:133], v[212:215], v[14:17]
	v_mfma_f32_16x16x32_bf16 v[10:13], v[138:141], v[212:215], v[10:13]
	s_setprio 0
	s_setprio 1
	v_mfma_f32_16x16x32_bf16 v[54:57], v[142:145], v[166:169], v[54:57]
	v_mfma_f32_16x16x32_bf16 v[50:53], v[158:161], v[166:169], v[50:53]
	v_mfma_f32_16x16x32_bf16 v[38:41], v[142:145], v[174:177], v[38:41]
	v_mfma_f32_16x16x32_bf16 v[34:37], v[158:161], v[174:177], v[34:37]
	v_mfma_f32_16x16x32_bf16 v[22:25], v[142:145], v[182:185], v[22:25]
	v_mfma_f32_16x16x32_bf16 v[18:21], v[158:161], v[182:185], v[18:21]
	v_mfma_f32_16x16x32_bf16 v[6:9], v[142:145], v[208:211], v[6:9]
	v_mfma_f32_16x16x32_bf16 v[2:5], v[158:161], v[208:211], v[2:5]
	v_mfma_f32_16x16x32_bf16 v[54:57], v[146:149], v[170:173], v[54:57]
	v_mfma_f32_16x16x32_bf16 v[50:53], v[162:165], v[170:173], v[50:53]
	v_mfma_f32_16x16x32_bf16 v[38:41], v[146:149], v[178:181], v[38:41]
	v_mfma_f32_16x16x32_bf16 v[34:37], v[162:165], v[178:181], v[34:37]
	v_mfma_f32_16x16x32_bf16 v[22:25], v[146:149], v[186:189], v[22:25]
	v_mfma_f32_16x16x32_bf16 v[18:21], v[162:165], v[186:189], v[18:21]
	v_mfma_f32_16x16x32_bf16 v[6:9], v[146:149], v[212:215], v[6:9]
	v_mfma_f32_16x16x32_bf16 v[2:5], v[162:165], v[212:215], v[2:5]
	s_setprio 0
	s_barrier
	s_add_i32 s4, 0, 0x18000
	s_add_i32 s5, 0, 0x1c000
	v_add_u32_e32 v138, s4, v231
	v_add_u32_e32 v162, s5, v231
	ds_read_b128 v[126:129], v138
	ds_read_b128 v[130:133], v138 offset:1024
	ds_read_b128 v[134:137], v138 offset:2048
	ds_read_b128 v[138:141], v138 offset:3072
	ds_read_b128 v[142:145], v162
	ds_read_b128 v[146:149], v162 offset:1024
	ds_read_b128 v[158:161], v162 offset:2048
	ds_read_b128 v[162:165], v162 offset:3072
	s_add_u32 s40, s40, 0x40000
	s_addc_u32 s41, s41, 0
	s_mov_b32 m0, s58
	v_lshl_add_u64 v[216:217], s[40:41], 0, v[202:203]
	ds_read_b128 v[166:169], v242 offset:32768
	ds_read_b128 v[170:173], v242 offset:33792
	ds_read_b128 v[174:177], v242 offset:34816
	ds_read_b128 v[178:181], v242 offset:35840
	ds_read_b128 v[182:185], v242 offset:36864
	ds_read_b128 v[186:189], v242 offset:37888
	ds_read_b128 v[208:211], v242 offset:38912
	ds_read_b128 v[212:215], v242 offset:39936
	global_load_lds_dwordx4 v[216:217], off
	v_lshl_add_u64 v[216:217], s[40:41], 0, v[192:193]
	s_mov_b32 m0, s59
	s_nop 0
	global_load_lds_dwordx4 v[216:217], off
	s_waitcnt vmcnt(8)
	s_waitcnt lgkmcnt(0)
	s_barrier
	s_setprio 1
	s_waitcnt lgkmcnt(0)
	v_mfma_f32_16x16x32_bf16 v[154:157], v[126:129], v[166:169], v[154:157]
	v_mfma_f32_16x16x32_bf16 v[150:153], v[134:137], v[166:169], v[150:153]
	v_mfma_f32_16x16x32_bf16 v[110:113], v[126:129], v[174:177], v[110:113]
	v_mfma_f32_16x16x32_bf16 v[106:109], v[134:137], v[174:177], v[106:109]
	v_mfma_f32_16x16x32_bf16 v[94:97], v[126:129], v[182:185], v[94:97]
	v_mfma_f32_16x16x32_bf16 v[90:93], v[134:137], v[182:185], v[90:93]
	v_mfma_f32_16x16x32_bf16 v[78:81], v[126:129], v[208:211], v[78:81]
	v_mfma_f32_16x16x32_bf16 v[74:77], v[134:137], v[208:211], v[74:77]
	v_mfma_f32_16x16x32_bf16 v[154:157], v[130:133], v[170:173], v[154:157]
	v_mfma_f32_16x16x32_bf16 v[150:153], v[138:141], v[170:173], v[150:153]
	v_mfma_f32_16x16x32_bf16 v[110:113], v[130:133], v[178:181], v[110:113]
	v_mfma_f32_16x16x32_bf16 v[106:109], v[138:141], v[178:181], v[106:109]
	v_mfma_f32_16x16x32_bf16 v[94:97], v[130:133], v[186:189], v[94:97]
	v_mfma_f32_16x16x32_bf16 v[90:93], v[138:141], v[186:189], v[90:93]
	v_mfma_f32_16x16x32_bf16 v[78:81], v[130:133], v[212:215], v[78:81]
	v_mfma_f32_16x16x32_bf16 v[74:77], v[138:141], v[212:215], v[74:77]
	s_setprio 0
	s_setprio 1
	v_mfma_f32_16x16x32_bf16 v[122:125], v[142:145], v[166:169], v[122:125]
	v_mfma_f32_16x16x32_bf16 v[114:117], v[158:161], v[166:169], v[114:117]
	v_mfma_f32_16x16x32_bf16 v[102:105], v[142:145], v[174:177], v[102:105]
	v_mfma_f32_16x16x32_bf16 v[98:101], v[158:161], v[174:177], v[98:101]
	v_mfma_f32_16x16x32_bf16 v[86:89], v[142:145], v[182:185], v[86:89]
	v_mfma_f32_16x16x32_bf16 v[82:85], v[158:161], v[182:185], v[82:85]
	v_mfma_f32_16x16x32_bf16 v[70:73], v[142:145], v[208:211], v[70:73]
	v_mfma_f32_16x16x32_bf16 v[66:69], v[158:161], v[208:211], v[66:69]
	v_mfma_f32_16x16x32_bf16 v[122:125], v[146:149], v[170:173], v[122:125]
	v_mfma_f32_16x16x32_bf16 v[114:117], v[162:165], v[170:173], v[114:117]
	v_mfma_f32_16x16x32_bf16 v[102:105], v[146:149], v[178:181], v[102:105]
	v_mfma_f32_16x16x32_bf16 v[98:101], v[162:165], v[178:181], v[98:101]
	v_mfma_f32_16x16x32_bf16 v[86:89], v[146:149], v[186:189], v[86:89]
	v_mfma_f32_16x16x32_bf16 v[82:85], v[162:165], v[186:189], v[82:85]
	v_mfma_f32_16x16x32_bf16 v[70:73], v[146:149], v[212:215], v[70:73]
	v_mfma_f32_16x16x32_bf16 v[66:69], v[162:165], v[212:215], v[66:69]
	s_setprio 0
	s_barrier
	s_add_i32 s4, s4, s51
	v_lshl_add_u64 v[194:195], v[194:195], 0, s[90:91]
	s_mov_b32 m0, s4
	ds_read_b128 v[166:169], v242 offset:49152
	ds_read_b128 v[170:173], v242 offset:50176
	ds_read_b128 v[174:177], v242 offset:51200
	ds_read_b128 v[178:181], v242 offset:52224
	ds_read_b128 v[182:185], v242 offset:53248
	ds_read_b128 v[186:189], v242 offset:54272
	ds_read_b128 v[208:211], v242 offset:55296
	ds_read_b128 v[212:215], v242 offset:56320
	global_load_lds_dwordx4 v[194:195], off
	s_add_i32 m0, s4, 0x2000
	s_add_u32 s38, s38, 0x40080
	v_lshl_add_u64 v[194:195], v[198:199], 0, s[90:91]
	s_addc_u32 s39, s39, 0
	s_add_i32 s4, s5, s51
	global_load_lds_dwordx4 v[194:195], off
	v_lshl_add_u64 v[194:195], s[38:39], 0, v[0:1]
	s_mov_b32 m0, s4
	s_nop 0
	global_load_lds_dwordx4 v[194:195], off
	v_lshl_add_u64 v[194:195], s[38:39], 0, v[190:191]
	s_add_i32 m0, s4, 0x2000
	s_nop 0
	global_load_lds_dwordx4 v[194:195], off
	v_lshl_add_u64 v[194:195], s[36:37], 0, v[202:203]
	s_mov_b32 m0, s68
	s_nop 0
	global_load_lds_dwordx4 v[194:195], off
	v_lshl_add_u64 v[194:195], s[36:37], 0, v[192:193]
	s_mov_b32 m0, s69
	s_nop 0
	global_load_lds_dwordx4 v[194:195], off
	s_waitcnt vmcnt(8)
	s_waitcnt lgkmcnt(0)
	s_barrier
	s_setprio 1
	s_waitcnt lgkmcnt(0)
	v_mfma_f32_16x16x32_bf16 v[62:65], v[126:129], v[166:169], v[62:65]
	v_mfma_f32_16x16x32_bf16 v[58:61], v[134:137], v[166:169], v[58:61]
	v_mfma_f32_16x16x32_bf16 v[46:49], v[126:129], v[174:177], v[46:49]
	v_mfma_f32_16x16x32_bf16 v[42:45], v[134:137], v[174:177], v[42:45]
	v_mfma_f32_16x16x32_bf16 v[30:33], v[126:129], v[182:185], v[30:33]
	v_mfma_f32_16x16x32_bf16 v[26:29], v[134:137], v[182:185], v[26:29]
	v_mfma_f32_16x16x32_bf16 v[14:17], v[126:129], v[208:211], v[14:17]
	v_mfma_f32_16x16x32_bf16 v[10:13], v[134:137], v[208:211], v[10:13]
	v_mfma_f32_16x16x32_bf16 v[62:65], v[130:133], v[170:173], v[62:65]
	v_mfma_f32_16x16x32_bf16 v[58:61], v[138:141], v[170:173], v[58:61]
	v_mfma_f32_16x16x32_bf16 v[46:49], v[130:133], v[178:181], v[46:49]
	v_mfma_f32_16x16x32_bf16 v[42:45], v[138:141], v[178:181], v[42:45]
	v_mfma_f32_16x16x32_bf16 v[30:33], v[130:133], v[186:189], v[30:33]
	v_mfma_f32_16x16x32_bf16 v[26:29], v[138:141], v[186:189], v[26:29]
	v_mfma_f32_16x16x32_bf16 v[14:17], v[130:133], v[212:215], v[14:17]
	v_mfma_f32_16x16x32_bf16 v[10:13], v[138:141], v[212:215], v[10:13]
	s_setprio 0
	s_setprio 1
	v_mfma_f32_16x16x32_bf16 v[54:57], v[142:145], v[166:169], v[54:57]
	v_mfma_f32_16x16x32_bf16 v[50:53], v[158:161], v[166:169], v[50:53]
	v_mfma_f32_16x16x32_bf16 v[38:41], v[142:145], v[174:177], v[38:41]
	v_mfma_f32_16x16x32_bf16 v[34:37], v[158:161], v[174:177], v[34:37]
	v_mfma_f32_16x16x32_bf16 v[22:25], v[142:145], v[182:185], v[22:25]
	v_mfma_f32_16x16x32_bf16 v[18:21], v[158:161], v[182:185], v[18:21]
	v_mfma_f32_16x16x32_bf16 v[6:9], v[142:145], v[208:211], v[6:9]
	v_mfma_f32_16x16x32_bf16 v[2:5], v[158:161], v[208:211], v[2:5]
	v_mfma_f32_16x16x32_bf16 v[54:57], v[146:149], v[170:173], v[54:57]
	v_mfma_f32_16x16x32_bf16 v[50:53], v[162:165], v[170:173], v[50:53]
	v_mfma_f32_16x16x32_bf16 v[38:41], v[146:149], v[178:181], v[38:41]
	v_mfma_f32_16x16x32_bf16 v[34:37], v[162:165], v[178:181], v[34:37]
	v_mfma_f32_16x16x32_bf16 v[22:25], v[146:149], v[186:189], v[22:25]
	v_mfma_f32_16x16x32_bf16 v[18:21], v[162:165], v[186:189], v[18:21]
	v_mfma_f32_16x16x32_bf16 v[6:9], v[146:149], v[212:215], v[6:9]
	v_mfma_f32_16x16x32_bf16 v[2:5], v[162:165], v[212:215], v[2:5]
	s_setprio 0
	s_add_i32 s86, s86, 2
	s_add_u32 s34, s34, 0x100
	s_addc_u32 s35, s35, 0
	s_add_u32 s4, s30, s34
	s_addc_u32 s5, s31, s35
	s_add_u32 s40, s4, 0x100
	s_addc_u32 s41, s5, 0
	s_add_u32 s38, s78, s34
	s_addc_u32 s39, s85, s35
	s_add_u32 s4, s4, 0x180
	s_addc_u32 s5, s5, 0
	s_add_i32 s65, 0, 0x10000
	s_add_i32 s87, 0, 0x14000
	s_cmp_gt_u32 s86, 13
	s_barrier
	s_cbranch_scc0 .Lg4k_body
	s_and_b64 vcc, exec, s[18:19]
	s_cbranch_vccz .LBB0_776
	s_barrier

.Lg5k_body:
	v_add_u32_e32 v162, s65, v152
	v_add_u32_e32 v178, s87, v152
	ds_read_b128 v[146:149], v162
	ds_read_b128 v[154:157], v162 offset:1024
	ds_read_b128 v[158:161], v162 offset:2048
	ds_read_b128 v[162:165], v162 offset:3072
	ds_read_b128 v[166:169], v178
	ds_read_b128 v[170:173], v178 offset:1024
	ds_read_b128 v[174:177], v178 offset:2048
	ds_read_b128 v[178:181], v178 offset:3072
	s_cmpk_eq_i32 s34, 0x700
	s_cselect_b32 s37, s76, s5
	s_cselect_b32 s36, s75, s4
	s_cselect_b32 s39, s23, s39
	s_cselect_b32 s38, s74, s38
	s_cselect_b32 s41, s25, s41
	s_cselect_b32 s40, s73, s40
	v_lshl_add_u64 v[194:195], v[142:143], 0, s[34:35]
	s_add_i32 m0, s56, 0xc000
	ds_read_b128 v[182:185], v153
	ds_read_b128 v[186:189], v153 offset:1024
	ds_read_b128 v[190:193], v153 offset:2048
	ds_read_b128 v[202:205], v153 offset:3072
	ds_read_b128 v[206:209], v153 offset:4096
	ds_read_b128 v[210:213], v153 offset:5120
	ds_read_b128 v[214:217], v153 offset:6144
	ds_read_b128 v[218:221], v153 offset:7168
	global_load_lds_dwordx4 v[194:195], off
	v_lshl_add_u64 v[194:195], v[144:145], 0, s[34:35]
	s_add_i32 m0, s56, 0xe000
	s_nop 0
	global_load_lds_dwordx4 v[194:195], off
	s_waitcnt vmcnt(8)
	s_waitcnt lgkmcnt(0)
	s_barrier
	s_setprio 1
	s_waitcnt lgkmcnt(0)
	v_mfma_f32_16x16x32_bf16 v[126:129], v[146:149], v[182:185], v[126:129]
	v_mfma_f32_16x16x32_bf16 v[122:125], v[158:161], v[182:185], v[122:125]
	v_mfma_f32_16x16x32_bf16 v[110:113], v[146:149], v[190:193], v[110:113]
	v_mfma_f32_16x16x32_bf16 v[106:109], v[158:161], v[190:193], v[106:109]
	v_mfma_f32_16x16x32_bf16 v[94:97], v[146:149], v[206:209], v[94:97]
	v_mfma_f32_16x16x32_bf16 v[90:93], v[158:161], v[206:209], v[90:93]
	v_mfma_f32_16x16x32_bf16 v[78:81], v[146:149], v[214:217], v[78:81]
	v_mfma_f32_16x16x32_bf16 v[74:77], v[158:161], v[214:217], v[74:77]
	v_mfma_f32_16x16x32_bf16 v[126:129], v[154:157], v[186:189], v[126:129]
	v_mfma_f32_16x16x32_bf16 v[122:125], v[162:165], v[186:189], v[122:125]
	v_mfma_f32_16x16x32_bf16 v[110:113], v[154:157], v[202:205], v[110:113]
	v_mfma_f32_16x16x32_bf16 v[106:109], v[162:165], v[202:205], v[106:109]
	v_mfma_f32_16x16x32_bf16 v[94:97], v[154:157], v[210:213], v[94:97]
	v_mfma_f32_16x16x32_bf16 v[90:93], v[162:165], v[210:213], v[90:93]
	v_mfma_f32_16x16x32_bf16 v[78:81], v[154:157], v[218:221], v[78:81]
	v_mfma_f32_16x16x32_bf16 v[74:77], v[162:165], v[218:221], v[74:77]
	s_setprio 0
	s_setprio 1
	v_mfma_f32_16x16x32_bf16 v[118:121], v[166:169], v[182:185], v[118:121]
	v_mfma_f32_16x16x32_bf16 v[114:117], v[174:177], v[182:185], v[114:117]
	v_mfma_f32_16x16x32_bf16 v[102:105], v[166:169], v[190:193], v[102:105]
	v_mfma_f32_16x16x32_bf16 v[98:101], v[174:177], v[190:193], v[98:101]
	v_mfma_f32_16x16x32_bf16 v[86:89], v[166:169], v[206:209], v[86:89]
	v_mfma_f32_16x16x32_bf16 v[82:85], v[174:177], v[206:209], v[82:85]
	v_mfma_f32_16x16x32_bf16 v[70:73], v[166:169], v[214:217], v[70:73]
	v_mfma_f32_16x16x32_bf16 v[66:69], v[174:177], v[214:217], v[66:69]
	v_mfma_f32_16x16x32_bf16 v[118:121], v[170:173], v[186:189], v[118:121]
	v_mfma_f32_16x16x32_bf16 v[114:117], v[178:181], v[186:189], v[114:117]
	v_mfma_f32_16x16x32_bf16 v[102:105], v[170:173], v[202:205], v[102:105]
	v_mfma_f32_16x16x32_bf16 v[98:101], v[178:181], v[202:205], v[98:101]
	v_mfma_f32_16x16x32_bf16 v[86:89], v[170:173], v[210:213], v[86:89]
	v_mfma_f32_16x16x32_bf16 v[82:85], v[178:181], v[210:213], v[82:85]
	v_mfma_f32_16x16x32_bf16 v[70:73], v[170:173], v[218:221], v[70:73]
	v_mfma_f32_16x16x32_bf16 v[66:69], v[178:181], v[218:221], v[66:69]
	s_setprio 0
	s_barrier
	s_add_i32 s4, s65, s51
	v_lshl_add_u64 v[194:195], s[38:39], 0, v[134:135]
	s_mov_b32 m0, s4
	ds_read_b128 v[182:185], v153 offset:16384
	ds_read_b128 v[186:189], v153 offset:17408
	ds_read_b128 v[190:193], v153 offset:18432
	ds_read_b128 v[202:205], v153 offset:19456
	ds_read_b128 v[206:209], v153 offset:20480
	ds_read_b128 v[210:213], v153 offset:21504
	ds_read_b128 v[214:217], v153 offset:22528
	ds_read_b128 v[218:221], v153 offset:23552
	global_load_lds_dwordx4 v[194:195], off
	s_add_i32 m0, s4, 0x2000
	s_add_u32 vcc_lo, s38, 0x40000
	v_lshl_add_u64 v[198:199], s[38:39], 0, v[130:131]
	s_addc_u32 vcc_hi, s39, 0
	s_add_i32 s4, s87, s51
	global_load_lds_dwordx4 v[198:199], off
	v_lshl_add_u64 v[222:223], vcc, 0, v[134:135]
	s_mov_b32 m0, s4
	s_nop 0
	global_load_lds_dwordx4 v[222:223], off
	v_lshl_add_u64 v[222:223], vcc, 0, v[130:131]
	s_add_i32 m0, s4, 0x2000
	s_nop 0
	global_load_lds_dwordx4 v[222:223], off
	v_lshl_add_u64 v[222:223], s[40:41], 0, v[136:137]
	s_mov_b32 m0, s56
	s_nop 0
	global_load_lds_dwordx4 v[222:223], off
	v_lshl_add_u64 v[222:223], s[40:41], 0, v[132:133]
	s_mov_b32 m0, s57
	s_nop 0
	global_load_lds_dwordx4 v[222:223], off
	s_waitcnt vmcnt(8)
	s_waitcnt lgkmcnt(0)
	s_barrier
	s_setprio 1
	s_waitcnt lgkmcnt(0)
	v_mfma_f32_16x16x32_bf16 v[62:65], v[146:149], v[182:185], v[62:65]
	v_mfma_f32_16x16x32_bf16 v[58:61], v[158:161], v[182:185], v[58:61]
	v_mfma_f32_16x16x32_bf16 v[46:49], v[146:149], v[190:193], v[46:49]
	v_mfma_f32_16x16x32_bf16 v[42:45], v[158:161], v[190:193], v[42:45]
	v_mfma_f32_16x16x32_bf16 v[30:33], v[146:149], v[206:209], v[30:33]
	v_mfma_f32_16x16x32_bf16 v[26:29], v[158:161], v[206:209], v[26:29]
	v_mfma_f32_16x16x32_bf16 v[14:17], v[146:149], v[214:217], v[14:17]
	v_mfma_f32_16x16x32_bf16 v[10:13], v[158:161], v[214:217], v[10:13]
	v_mfma_f32_16x16x32_bf16 v[62:65], v[154:157], v[186:189], v[62:65]
	v_mfma_f32_16x16x32_bf16 v[58:61], v[162:165], v[186:189], v[58:61]
	v_mfma_f32_16x16x32_bf16 v[46:49], v[154:157], v[202:205], v[46:49]
	v_mfma_f32_16x16x32_bf16 v[42:45], v[162:165], v[202:205], v[42:45]
	v_mfma_f32_16x16x32_bf16 v[30:33], v[154:157], v[210:213], v[30:33]
	v_mfma_f32_16x16x32_bf16 v[26:29], v[162:165], v[210:213], v[26:29]
	v_mfma_f32_16x16x32_bf16 v[14:17], v[154:157], v[218:221], v[14:17]
	v_mfma_f32_16x16x32_bf16 v[10:13], v[162:165], v[218:221], v[10:13]
	s_setprio 0
	s_setprio 1
	v_mfma_f32_16x16x32_bf16 v[54:57], v[166:169], v[182:185], v[54:57]
	v_mfma_f32_16x16x32_bf16 v[50:53], v[174:177], v[182:185], v[50:53]
	v_mfma_f32_16x16x32_bf16 v[38:41], v[166:169], v[190:193], v[38:41]
	v_mfma_f32_16x16x32_bf16 v[34:37], v[174:177], v[190:193], v[34:37]
	v_mfma_f32_16x16x32_bf16 v[22:25], v[166:169], v[206:209], v[22:25]
	v_mfma_f32_16x16x32_bf16 v[18:21], v[174:177], v[206:209], v[18:21]
	v_mfma_f32_16x16x32_bf16 v[6:9], v[166:169], v[214:217], v[6:9]
	v_mfma_f32_16x16x32_bf16 v[2:5], v[174:177], v[214:217], v[2:5]
	v_mfma_f32_16x16x32_bf16 v[54:57], v[170:173], v[186:189], v[54:57]
	v_mfma_f32_16x16x32_bf16 v[50:53], v[178:181], v[186:189], v[50:53]
	v_mfma_f32_16x16x32_bf16 v[38:41], v[170:173], v[202:205], v[38:41]
	v_mfma_f32_16x16x32_bf16 v[34:37], v[178:181], v[202:205], v[34:37]
	v_mfma_f32_16x16x32_bf16 v[22:25], v[170:173], v[210:213], v[22:25]
	v_mfma_f32_16x16x32_bf16 v[18:21], v[178:181], v[210:213], v[18:21]
	v_mfma_f32_16x16x32_bf16 v[6:9], v[170:173], v[218:221], v[6:9]
	v_mfma_f32_16x16x32_bf16 v[2:5], v[178:181], v[218:221], v[2:5]
	s_setprio 0
	s_barrier
	s_add_i32 s4, 0, 0x18000
	s_add_i32 s5, 0, 0x1c000
	v_add_u32_e32 v162, s4, v152
	v_add_u32_e32 v178, s5, v152
	ds_read_b128 v[146:149], v162
	ds_read_b128 v[154:157], v162 offset:1024
	ds_read_b128 v[158:161], v162 offset:2048
	ds_read_b128 v[162:165], v162 offset:3072
	ds_read_b128 v[166:169], v178
	ds_read_b128 v[170:173], v178 offset:1024
	ds_read_b128 v[174:177], v178 offset:2048
	ds_read_b128 v[178:181], v178 offset:3072
	s_add_u32 s40, s40, 0x40000
	s_addc_u32 s41, s41, 0
	s_mov_b32 m0, s58
	v_lshl_add_u64 v[222:223], s[40:41], 0, v[136:137]
	ds_read_b128 v[182:185], v153 offset:32768
	ds_read_b128 v[186:189], v153 offset:33792
	ds_read_b128 v[190:193], v153 offset:34816
	ds_read_b128 v[202:205], v153 offset:35840
	ds_read_b128 v[206:209], v153 offset:36864
	ds_read_b128 v[210:213], v153 offset:37888
	ds_read_b128 v[214:217], v153 offset:38912
	ds_read_b128 v[218:221], v153 offset:39936
	global_load_lds_dwordx4 v[222:223], off
	v_lshl_add_u64 v[222:223], s[40:41], 0, v[132:133]
	s_mov_b32 m0, s59
	s_nop 0
	global_load_lds_dwordx4 v[222:223], off
	s_waitcnt vmcnt(8)
	s_waitcnt lgkmcnt(0)
	s_barrier
	s_setprio 1
	s_waitcnt lgkmcnt(0)
	v_mfma_f32_16x16x32_bf16 v[126:129], v[146:149], v[182:185], v[126:129]
	v_mfma_f32_16x16x32_bf16 v[122:125], v[158:161], v[182:185], v[122:125]
	v_mfma_f32_16x16x32_bf16 v[110:113], v[146:149], v[190:193], v[110:113]
	v_mfma_f32_16x16x32_bf16 v[106:109], v[158:161], v[190:193], v[106:109]
	v_mfma_f32_16x16x32_bf16 v[94:97], v[146:149], v[206:209], v[94:97]
	v_mfma_f32_16x16x32_bf16 v[90:93], v[158:161], v[206:209], v[90:93]
	v_mfma_f32_16x16x32_bf16 v[78:81], v[146:149], v[214:217], v[78:81]
	v_mfma_f32_16x16x32_bf16 v[74:77], v[158:161], v[214:217], v[74:77]
	v_mfma_f32_16x16x32_bf16 v[126:129], v[154:157], v[186:189], v[126:129]
	v_mfma_f32_16x16x32_bf16 v[122:125], v[162:165], v[186:189], v[122:125]
	v_mfma_f32_16x16x32_bf16 v[110:113], v[154:157], v[202:205], v[110:113]
	v_mfma_f32_16x16x32_bf16 v[106:109], v[162:165], v[202:205], v[106:109]
	v_mfma_f32_16x16x32_bf16 v[94:97], v[154:157], v[210:213], v[94:97]
	v_mfma_f32_16x16x32_bf16 v[90:93], v[162:165], v[210:213], v[90:93]
	v_mfma_f32_16x16x32_bf16 v[78:81], v[154:157], v[218:221], v[78:81]
	v_mfma_f32_16x16x32_bf16 v[74:77], v[162:165], v[218:221], v[74:77]
	s_setprio 0
	s_setprio 1
	v_mfma_f32_16x16x32_bf16 v[118:121], v[166:169], v[182:185], v[118:121]
	v_mfma_f32_16x16x32_bf16 v[114:117], v[174:177], v[182:185], v[114:117]
	v_mfma_f32_16x16x32_bf16 v[102:105], v[166:169], v[190:193], v[102:105]
	v_mfma_f32_16x16x32_bf16 v[98:101], v[174:177], v[190:193], v[98:101]
	v_mfma_f32_16x16x32_bf16 v[86:89], v[166:169], v[206:209], v[86:89]
	v_mfma_f32_16x16x32_bf16 v[82:85], v[174:177], v[206:209], v[82:85]
	v_mfma_f32_16x16x32_bf16 v[70:73], v[166:169], v[214:217], v[70:73]
	v_mfma_f32_16x16x32_bf16 v[66:69], v[174:177], v[214:217], v[66:69]
	v_mfma_f32_16x16x32_bf16 v[118:121], v[170:173], v[186:189], v[118:121]
	v_mfma_f32_16x16x32_bf16 v[114:117], v[178:181], v[186:189], v[114:117]
	v_mfma_f32_16x16x32_bf16 v[102:105], v[170:173], v[202:205], v[102:105]
	v_mfma_f32_16x16x32_bf16 v[98:101], v[178:181], v[202:205], v[98:101]
	v_mfma_f32_16x16x32_bf16 v[86:89], v[170:173], v[210:213], v[86:89]
	v_mfma_f32_16x16x32_bf16 v[82:85], v[178:181], v[210:213], v[82:85]
	v_mfma_f32_16x16x32_bf16 v[70:73], v[170:173], v[218:221], v[70:73]
	v_mfma_f32_16x16x32_bf16 v[66:69], v[178:181], v[218:221], v[66:69]
	s_setprio 0
	s_barrier
	s_add_i32 s4, s4, s51
	v_lshl_add_u64 v[194:195], v[194:195], 0, s[90:91]
	s_mov_b32 m0, s4
	ds_read_b128 v[182:185], v153 offset:49152
	ds_read_b128 v[186:189], v153 offset:50176
	ds_read_b128 v[190:193], v153 offset:51200
	ds_read_b128 v[202:205], v153 offset:52224
	ds_read_b128 v[206:209], v153 offset:53248
	ds_read_b128 v[210:213], v153 offset:54272
	ds_read_b128 v[214:217], v153 offset:55296
	ds_read_b128 v[218:221], v153 offset:56320
	global_load_lds_dwordx4 v[194:195], off
	s_add_i32 m0, s4, 0x2000
	s_add_u32 s38, s38, 0x40080
	v_lshl_add_u64 v[194:195], v[198:199], 0, s[90:91]
	s_addc_u32 s39, s39, 0
	s_add_i32 s4, s5, s51
	global_load_lds_dwordx4 v[194:195], off
	v_lshl_add_u64 v[194:195], s[38:39], 0, v[134:135]
	s_mov_b32 m0, s4
	s_nop 0
	global_load_lds_dwordx4 v[194:195], off
	v_lshl_add_u64 v[194:195], s[38:39], 0, v[130:131]
	s_add_i32 m0, s4, 0x2000
	s_nop 0
	global_load_lds_dwordx4 v[194:195], off
	v_lshl_add_u64 v[194:195], s[36:37], 0, v[136:137]
	s_mov_b32 m0, s68
	s_nop 0
	global_load_lds_dwordx4 v[194:195], off
	v_lshl_add_u64 v[194:195], s[36:37], 0, v[132:133]
	s_mov_b32 m0, s69
	s_nop 0
	global_load_lds_dwordx4 v[194:195], off
	s_waitcnt vmcnt(8)
	s_waitcnt lgkmcnt(0)
	s_barrier
	s_setprio 1
	s_waitcnt lgkmcnt(0)
	v_mfma_f32_16x16x32_bf16 v[62:65], v[146:149], v[182:185], v[62:65]
	v_mfma_f32_16x16x32_bf16 v[58:61], v[158:161], v[182:185], v[58:61]
	v_mfma_f32_16x16x32_bf16 v[46:49], v[146:149], v[190:193], v[46:49]
	v_mfma_f32_16x16x32_bf16 v[42:45], v[158:161], v[190:193], v[42:45]
	v_mfma_f32_16x16x32_bf16 v[30:33], v[146:149], v[206:209], v[30:33]
	v_mfma_f32_16x16x32_bf16 v[26:29], v[158:161], v[206:209], v[26:29]
	v_mfma_f32_16x16x32_bf16 v[14:17], v[146:149], v[214:217], v[14:17]
	v_mfma_f32_16x16x32_bf16 v[10:13], v[158:161], v[214:217], v[10:13]
	v_mfma_f32_16x16x32_bf16 v[62:65], v[154:157], v[186:189], v[62:65]
	v_mfma_f32_16x16x32_bf16 v[58:61], v[162:165], v[186:189], v[58:61]
	v_mfma_f32_16x16x32_bf16 v[46:49], v[154:157], v[202:205], v[46:49]
	v_mfma_f32_16x16x32_bf16 v[42:45], v[162:165], v[202:205], v[42:45]
	v_mfma_f32_16x16x32_bf16 v[30:33], v[154:157], v[210:213], v[30:33]
	v_mfma_f32_16x16x32_bf16 v[26:29], v[162:165], v[210:213], v[26:29]
	v_mfma_f32_16x16x32_bf16 v[14:17], v[154:157], v[218:221], v[14:17]
	v_mfma_f32_16x16x32_bf16 v[10:13], v[162:165], v[218:221], v[10:13]
	s_setprio 0
	s_setprio 1
	v_mfma_f32_16x16x32_bf16 v[54:57], v[166:169], v[182:185], v[54:57]
	v_mfma_f32_16x16x32_bf16 v[50:53], v[174:177], v[182:185], v[50:53]
	v_mfma_f32_16x16x32_bf16 v[38:41], v[166:169], v[190:193], v[38:41]
	v_mfma_f32_16x16x32_bf16 v[34:37], v[174:177], v[190:193], v[34:37]
	v_mfma_f32_16x16x32_bf16 v[22:25], v[166:169], v[206:209], v[22:25]
	v_mfma_f32_16x16x32_bf16 v[18:21], v[174:177], v[206:209], v[18:21]
	v_mfma_f32_16x16x32_bf16 v[6:9], v[166:169], v[214:217], v[6:9]
	v_mfma_f32_16x16x32_bf16 v[2:5], v[174:177], v[214:217], v[2:5]
	v_mfma_f32_16x16x32_bf16 v[54:57], v[170:173], v[186:189], v[54:57]
	v_mfma_f32_16x16x32_bf16 v[50:53], v[178:181], v[186:189], v[50:53]
	v_mfma_f32_16x16x32_bf16 v[38:41], v[170:173], v[202:205], v[38:41]
	v_mfma_f32_16x16x32_bf16 v[34:37], v[178:181], v[202:205], v[34:37]
	v_mfma_f32_16x16x32_bf16 v[22:25], v[170:173], v[210:213], v[22:25]
	v_mfma_f32_16x16x32_bf16 v[18:21], v[178:181], v[210:213], v[18:21]
	v_mfma_f32_16x16x32_bf16 v[6:9], v[170:173], v[218:221], v[6:9]
	v_mfma_f32_16x16x32_bf16 v[2:5], v[178:181], v[218:221], v[2:5]
	s_setprio 0
	s_add_i32 s86, s86, 2
	s_add_u32 s34, s34, 0x100
	s_addc_u32 s35, s35, 0
	s_add_u32 s4, s30, s34
	s_addc_u32 s5, s31, s35
	s_add_u32 s40, s4, 0x100
	s_addc_u32 s41, s5, 0
	s_add_u32 s38, s78, s34
	s_addc_u32 s39, s85, s35
	s_add_u32 s4, s4, 0x180
	s_addc_u32 s5, s5, 0
	s_add_i32 s65, 0, 0x10000
	s_add_i32 s87, 0, 0x14000
	s_cmp_gt_u32 s86, 13
	s_barrier
	s_cbranch_scc0 .Lg5k_body
	s_and_b64 vcc, exec, s[20:21]
	s_cbranch_vccz .LBB0_864
	s_barrier

.Lg6ak_body:
	v_add_u32_e32 v138, s85, v231
	v_add_u32_e32 v162, vcc_lo, v231
	ds_read_b128 v[126:129], v138
	ds_read_b128 v[130:133], v138 offset:1024
	ds_read_b128 v[134:137], v138 offset:2048
	ds_read_b128 v[138:141], v138 offset:3072
	ds_read_b128 v[142:145], v162
	ds_read_b128 v[146:149], v162 offset:1024
	ds_read_b128 v[158:161], v162 offset:2048
	ds_read_b128 v[162:165], v162 offset:3072
	s_cmpk_eq_i32 s36, 0x1f00
	s_cselect_b32 s39, s75, s5
	s_cselect_b32 s38, s74, s4
	s_cselect_b32 s41, s25, s41
	s_cselect_b32 s40, s73, s40
	s_cselect_b32 s43, s27, s43
	s_cselect_b32 s42, s72, s42
	v_lshl_add_u64 v[194:195], v[118:119], 0, s[36:37]
	s_add_i32 m0, s58, 0xc000
	ds_read_b128 v[166:169], v242
	ds_read_b128 v[170:173], v242 offset:1024
	ds_read_b128 v[174:177], v242 offset:2048
	ds_read_b128 v[178:181], v242 offset:3072
	ds_read_b128 v[182:185], v242 offset:4096
	ds_read_b128 v[186:189], v242 offset:5120
	ds_read_b128 v[208:211], v242 offset:6144
	ds_read_b128 v[212:215], v242 offset:7168
	global_load_lds_dwordx4 v[194:195], off
	v_lshl_add_u64 v[194:195], v[120:121], 0, s[36:37]
	s_add_i32 m0, s58, 0xe000
	s_nop 0
	global_load_lds_dwordx4 v[194:195], off
	s_waitcnt vmcnt(8)
	s_waitcnt lgkmcnt(0)
	s_barrier
	s_setprio 1
	s_waitcnt lgkmcnt(0)
	v_mfma_f32_16x16x32_bf16 v[154:157], v[126:129], v[166:169], v[154:157]
	v_mfma_f32_16x16x32_bf16 v[150:153], v[134:137], v[166:169], v[150:153]
	v_mfma_f32_16x16x32_bf16 v[110:113], v[126:129], v[174:177], v[110:113]
	v_mfma_f32_16x16x32_bf16 v[106:109], v[134:137], v[174:177], v[106:109]
	v_mfma_f32_16x16x32_bf16 v[94:97], v[126:129], v[182:185], v[94:97]
	v_mfma_f32_16x16x32_bf16 v[90:93], v[134:137], v[182:185], v[90:93]
	v_mfma_f32_16x16x32_bf16 v[78:81], v[126:129], v[208:211], v[78:81]
	v_mfma_f32_16x16x32_bf16 v[74:77], v[134:137], v[208:211], v[74:77]
	v_mfma_f32_16x16x32_bf16 v[154:157], v[130:133], v[170:173], v[154:157]
	v_mfma_f32_16x16x32_bf16 v[150:153], v[138:141], v[170:173], v[150:153]
	v_mfma_f32_16x16x32_bf16 v[110:113], v[130:133], v[178:181], v[110:113]
	v_mfma_f32_16x16x32_bf16 v[106:109], v[138:141], v[178:181], v[106:109]
	v_mfma_f32_16x16x32_bf16 v[94:97], v[130:133], v[186:189], v[94:97]
	v_mfma_f32_16x16x32_bf16 v[90:93], v[138:141], v[186:189], v[90:93]
	v_mfma_f32_16x16x32_bf16 v[78:81], v[130:133], v[212:215], v[78:81]
	v_mfma_f32_16x16x32_bf16 v[74:77], v[138:141], v[212:215], v[74:77]
	s_setprio 0
	s_setprio 1
	v_mfma_f32_16x16x32_bf16 v[122:125], v[142:145], v[166:169], v[122:125]
	v_mfma_f32_16x16x32_bf16 v[114:117], v[158:161], v[166:169], v[114:117]
	v_mfma_f32_16x16x32_bf16 v[102:105], v[142:145], v[174:177], v[102:105]
	v_mfma_f32_16x16x32_bf16 v[98:101], v[158:161], v[174:177], v[98:101]
	v_mfma_f32_16x16x32_bf16 v[86:89], v[142:145], v[182:185], v[86:89]
	v_mfma_f32_16x16x32_bf16 v[82:85], v[158:161], v[182:185], v[82:85]
	v_mfma_f32_16x16x32_bf16 v[70:73], v[142:145], v[208:211], v[70:73]
	v_mfma_f32_16x16x32_bf16 v[66:69], v[158:161], v[208:211], v[66:69]
	v_mfma_f32_16x16x32_bf16 v[122:125], v[146:149], v[170:173], v[122:125]
	v_mfma_f32_16x16x32_bf16 v[114:117], v[162:165], v[170:173], v[114:117]
	v_mfma_f32_16x16x32_bf16 v[102:105], v[146:149], v[178:181], v[102:105]
	v_mfma_f32_16x16x32_bf16 v[98:101], v[162:165], v[178:181], v[98:101]
	v_mfma_f32_16x16x32_bf16 v[86:89], v[146:149], v[186:189], v[86:89]
	v_mfma_f32_16x16x32_bf16 v[82:85], v[162:165], v[186:189], v[82:85]
	v_mfma_f32_16x16x32_bf16 v[70:73], v[146:149], v[212:215], v[70:73]
	v_mfma_f32_16x16x32_bf16 v[66:69], v[162:165], v[212:215], v[66:69]
	s_setprio 0
	s_barrier
	s_add_i32 s4, s85, s57
	v_lshl_add_u64 v[194:195], s[40:41], 0, v[0:1]
	s_mov_b32 m0, s4
	ds_read_b128 v[166:169], v242 offset:16384
	ds_read_b128 v[170:173], v242 offset:17408
	ds_read_b128 v[174:177], v242 offset:18432
	ds_read_b128 v[178:181], v242 offset:19456
	ds_read_b128 v[182:185], v242 offset:20480
	ds_read_b128 v[186:189], v242 offset:21504
	ds_read_b128 v[208:211], v242 offset:22528
	ds_read_b128 v[212:215], v242 offset:23552
	global_load_lds_dwordx4 v[194:195], off
	s_add_i32 m0, s4, 0x2000
	s_add_u32 s86, s40, 0x100000
	v_lshl_add_u64 v[198:199], s[40:41], 0, v[190:191]
	s_addc_u32 s87, s41, 0
	s_add_i32 s4, vcc_lo, s57
	global_load_lds_dwordx4 v[198:199], off
	v_lshl_add_u64 v[216:217], s[86:87], 0, v[0:1]
	s_mov_b32 m0, s4
	s_nop 0
	global_load_lds_dwordx4 v[216:217], off
	v_lshl_add_u64 v[216:217], s[86:87], 0, v[190:191]
	s_add_i32 m0, s4, 0x2000
	s_nop 0
	global_load_lds_dwordx4 v[216:217], off
	v_lshl_add_u64 v[216:217], s[42:43], 0, v[202:203]
	s_mov_b32 m0, s58
	s_nop 0
	global_load_lds_dwordx4 v[216:217], off
	v_lshl_add_u64 v[216:217], s[42:43], 0, v[192:193]
	s_mov_b32 m0, s59
	s_nop 0
	global_load_lds_dwordx4 v[216:217], off
	s_waitcnt vmcnt(8)
	s_waitcnt lgkmcnt(0)
	s_barrier
	s_setprio 1
	s_waitcnt lgkmcnt(0)
	v_mfma_f32_16x16x32_bf16 v[62:65], v[126:129], v[166:169], v[62:65]
	v_mfma_f32_16x16x32_bf16 v[58:61], v[134:137], v[166:169], v[58:61]
	v_mfma_f32_16x16x32_bf16 v[46:49], v[126:129], v[174:177], v[46:49]
	v_mfma_f32_16x16x32_bf16 v[42:45], v[134:137], v[174:177], v[42:45]
	v_mfma_f32_16x16x32_bf16 v[30:33], v[126:129], v[182:185], v[30:33]
	v_mfma_f32_16x16x32_bf16 v[26:29], v[134:137], v[182:185], v[26:29]
	v_mfma_f32_16x16x32_bf16 v[14:17], v[126:129], v[208:211], v[14:17]
	v_mfma_f32_16x16x32_bf16 v[10:13], v[134:137], v[208:211], v[10:13]
	v_mfma_f32_16x16x32_bf16 v[62:65], v[130:133], v[170:173], v[62:65]
	v_mfma_f32_16x16x32_bf16 v[58:61], v[138:141], v[170:173], v[58:61]
	v_mfma_f32_16x16x32_bf16 v[46:49], v[130:133], v[178:181], v[46:49]
	v_mfma_f32_16x16x32_bf16 v[42:45], v[138:141], v[178:181], v[42:45]
	v_mfma_f32_16x16x32_bf16 v[30:33], v[130:133], v[186:189], v[30:33]
	v_mfma_f32_16x16x32_bf16 v[26:29], v[138:141], v[186:189], v[26:29]
	v_mfma_f32_16x16x32_bf16 v[14:17], v[130:133], v[212:215], v[14:17]
	v_mfma_f32_16x16x32_bf16 v[10:13], v[138:141], v[212:215], v[10:13]
	s_setprio 0
	s_setprio 1
	v_mfma_f32_16x16x32_bf16 v[54:57], v[142:145], v[166:169], v[54:57]
	v_mfma_f32_16x16x32_bf16 v[50:53], v[158:161], v[166:169], v[50:53]
	v_mfma_f32_16x16x32_bf16 v[38:41], v[142:145], v[174:177], v[38:41]
	v_mfma_f32_16x16x32_bf16 v[34:37], v[158:161], v[174:177], v[34:37]
	v_mfma_f32_16x16x32_bf16 v[22:25], v[142:145], v[182:185], v[22:25]
	v_mfma_f32_16x16x32_bf16 v[18:21], v[158:161], v[182:185], v[18:21]
	v_mfma_f32_16x16x32_bf16 v[6:9], v[142:145], v[208:211], v[6:9]
	v_mfma_f32_16x16x32_bf16 v[2:5], v[158:161], v[208:211], v[2:5]
	v_mfma_f32_16x16x32_bf16 v[54:57], v[146:149], v[170:173], v[54:57]
	v_mfma_f32_16x16x32_bf16 v[50:53], v[162:165], v[170:173], v[50:53]
	v_mfma_f32_16x16x32_bf16 v[38:41], v[146:149], v[178:181], v[38:41]
	v_mfma_f32_16x16x32_bf16 v[34:37], v[162:165], v[178:181], v[34:37]
	v_mfma_f32_16x16x32_bf16 v[22:25], v[146:149], v[186:189], v[22:25]
	v_mfma_f32_16x16x32_bf16 v[18:21], v[162:165], v[186:189], v[18:21]
	v_mfma_f32_16x16x32_bf16 v[6:9], v[146:149], v[212:215], v[6:9]
	v_mfma_f32_16x16x32_bf16 v[2:5], v[162:165], v[212:215], v[2:5]
	s_setprio 0
	s_barrier
	s_add_i32 s4, 0, 0x18000
	s_add_i32 s5, 0, 0x1c000
	v_add_u32_e32 v138, s4, v231
	v_add_u32_e32 v162, s5, v231
	ds_read_b128 v[126:129], v138
	ds_read_b128 v[130:133], v138 offset:1024
	ds_read_b128 v[134:137], v138 offset:2048
	ds_read_b128 v[138:141], v138 offset:3072
	ds_read_b128 v[142:145], v162
	ds_read_b128 v[146:149], v162 offset:1024
	ds_read_b128 v[158:161], v162 offset:2048
	ds_read_b128 v[162:165], v162 offset:3072
	s_add_u32 s42, s42, 0x100000
	s_addc_u32 s43, s43, 0
	s_mov_b32 m0, s65
	v_lshl_add_u64 v[216:217], s[42:43], 0, v[202:203]
	ds_read_b128 v[166:169], v242 offset:32768
	ds_read_b128 v[170:173], v242 offset:33792
	ds_read_b128 v[174:177], v242 offset:34816
	ds_read_b128 v[178:181], v242 offset:35840
	ds_read_b128 v[182:185], v242 offset:36864
	ds_read_b128 v[186:189], v242 offset:37888
	ds_read_b128 v[208:211], v242 offset:38912
	ds_read_b128 v[212:215], v242 offset:39936
	global_load_lds_dwordx4 v[216:217], off
	v_lshl_add_u64 v[216:217], s[42:43], 0, v[192:193]
	s_mov_b32 m0, s68
	s_nop 0
	global_load_lds_dwordx4 v[216:217], off
	s_waitcnt vmcnt(8)
	s_waitcnt lgkmcnt(0)
	s_barrier
	s_setprio 1
	s_waitcnt lgkmcnt(0)
	v_mfma_f32_16x16x32_bf16 v[154:157], v[126:129], v[166:169], v[154:157]
	v_mfma_f32_16x16x32_bf16 v[150:153], v[134:137], v[166:169], v[150:153]
	v_mfma_f32_16x16x32_bf16 v[110:113], v[126:129], v[174:177], v[110:113]
	v_mfma_f32_16x16x32_bf16 v[106:109], v[134:137], v[174:177], v[106:109]
	v_mfma_f32_16x16x32_bf16 v[94:97], v[126:129], v[182:185], v[94:97]
	v_mfma_f32_16x16x32_bf16 v[90:93], v[134:137], v[182:185], v[90:93]
	v_mfma_f32_16x16x32_bf16 v[78:81], v[126:129], v[208:211], v[78:81]
	v_mfma_f32_16x16x32_bf16 v[74:77], v[134:137], v[208:211], v[74:77]
	v_mfma_f32_16x16x32_bf16 v[154:157], v[130:133], v[170:173], v[154:157]
	v_mfma_f32_16x16x32_bf16 v[150:153], v[138:141], v[170:173], v[150:153]
	v_mfma_f32_16x16x32_bf16 v[110:113], v[130:133], v[178:181], v[110:113]
	v_mfma_f32_16x16x32_bf16 v[106:109], v[138:141], v[178:181], v[106:109]
	v_mfma_f32_16x16x32_bf16 v[94:97], v[130:133], v[186:189], v[94:97]
	v_mfma_f32_16x16x32_bf16 v[90:93], v[138:141], v[186:189], v[90:93]
	v_mfma_f32_16x16x32_bf16 v[78:81], v[130:133], v[212:215], v[78:81]
	v_mfma_f32_16x16x32_bf16 v[74:77], v[138:141], v[212:215], v[74:77]
	s_setprio 0
	s_setprio 1
	v_mfma_f32_16x16x32_bf16 v[122:125], v[142:145], v[166:169], v[122:125]
	v_mfma_f32_16x16x32_bf16 v[114:117], v[158:161], v[166:169], v[114:117]
	v_mfma_f32_16x16x32_bf16 v[102:105], v[142:145], v[174:177], v[102:105]
	v_mfma_f32_16x16x32_bf16 v[98:101], v[158:161], v[174:177], v[98:101]
	v_mfma_f32_16x16x32_bf16 v[86:89], v[142:145], v[182:185], v[86:89]
	v_mfma_f32_16x16x32_bf16 v[82:85], v[158:161], v[182:185], v[82:85]
	v_mfma_f32_16x16x32_bf16 v[70:73], v[142:145], v[208:211], v[70:73]
	v_mfma_f32_16x16x32_bf16 v[66:69], v[158:161], v[208:211], v[66:69]
	v_mfma_f32_16x16x32_bf16 v[122:125], v[146:149], v[170:173], v[122:125]
	v_mfma_f32_16x16x32_bf16 v[114:117], v[162:165], v[170:173], v[114:117]
	v_mfma_f32_16x16x32_bf16 v[102:105], v[146:149], v[178:181], v[102:105]
	v_mfma_f32_16x16x32_bf16 v[98:101], v[162:165], v[178:181], v[98:101]
	v_mfma_f32_16x16x32_bf16 v[86:89], v[146:149], v[186:189], v[86:89]
	v_mfma_f32_16x16x32_bf16 v[82:85], v[162:165], v[186:189], v[82:85]
	v_mfma_f32_16x16x32_bf16 v[70:73], v[146:149], v[212:215], v[70:73]
	v_mfma_f32_16x16x32_bf16 v[66:69], v[162:165], v[212:215], v[66:69]
	s_setprio 0
	s_barrier
	s_add_i32 s4, s4, s57
	v_lshl_add_u64 v[194:195], v[194:195], 0, s[90:91]
	s_mov_b32 m0, s4
	ds_read_b128 v[166:169], v242 offset:49152
	ds_read_b128 v[170:173], v242 offset:50176
	ds_read_b128 v[174:177], v242 offset:51200
	ds_read_b128 v[178:181], v242 offset:52224
	ds_read_b128 v[182:185], v242 offset:53248
	ds_read_b128 v[186:189], v242 offset:54272
	ds_read_b128 v[208:211], v242 offset:55296
	ds_read_b128 v[212:215], v242 offset:56320
	global_load_lds_dwordx4 v[194:195], off
	s_add_i32 m0, s4, 0x2000
	s_add_u32 s40, s40, 0x100080
	v_lshl_add_u64 v[194:195], v[198:199], 0, s[90:91]
	s_addc_u32 s41, s41, 0
	s_add_i32 s4, s5, s57
	global_load_lds_dwordx4 v[194:195], off
	v_lshl_add_u64 v[194:195], s[40:41], 0, v[0:1]
	s_mov_b32 m0, s4
	s_nop 0
	global_load_lds_dwordx4 v[194:195], off
	v_lshl_add_u64 v[194:195], s[40:41], 0, v[190:191]
	s_add_i32 m0, s4, 0x2000
	s_nop 0
	global_load_lds_dwordx4 v[194:195], off
	v_lshl_add_u64 v[194:195], s[38:39], 0, v[202:203]
	s_mov_b32 m0, s54
	s_nop 0
	global_load_lds_dwordx4 v[194:195], off
	v_lshl_add_u64 v[194:195], s[38:39], 0, v[192:193]
	s_mov_b32 m0, s55
	s_nop 0
	global_load_lds_dwordx4 v[194:195], off
	s_waitcnt vmcnt(8)
	s_waitcnt lgkmcnt(0)
	s_barrier
	s_setprio 1
	s_waitcnt lgkmcnt(0)
	v_mfma_f32_16x16x32_bf16 v[62:65], v[126:129], v[166:169], v[62:65]
	v_mfma_f32_16x16x32_bf16 v[58:61], v[134:137], v[166:169], v[58:61]
	v_mfma_f32_16x16x32_bf16 v[46:49], v[126:129], v[174:177], v[46:49]
	v_mfma_f32_16x16x32_bf16 v[42:45], v[134:137], v[174:177], v[42:45]
	v_mfma_f32_16x16x32_bf16 v[30:33], v[126:129], v[182:185], v[30:33]
	v_mfma_f32_16x16x32_bf16 v[26:29], v[134:137], v[182:185], v[26:29]
	v_mfma_f32_16x16x32_bf16 v[14:17], v[126:129], v[208:211], v[14:17]
	v_mfma_f32_16x16x32_bf16 v[10:13], v[134:137], v[208:211], v[10:13]
	v_mfma_f32_16x16x32_bf16 v[62:65], v[130:133], v[170:173], v[62:65]
	v_mfma_f32_16x16x32_bf16 v[58:61], v[138:141], v[170:173], v[58:61]
	v_mfma_f32_16x16x32_bf16 v[46:49], v[130:133], v[178:181], v[46:49]
	v_mfma_f32_16x16x32_bf16 v[42:45], v[138:141], v[178:181], v[42:45]
	v_mfma_f32_16x16x32_bf16 v[30:33], v[130:133], v[186:189], v[30:33]
	v_mfma_f32_16x16x32_bf16 v[26:29], v[138:141], v[186:189], v[26:29]
	v_mfma_f32_16x16x32_bf16 v[14:17], v[130:133], v[212:215], v[14:17]
	v_mfma_f32_16x16x32_bf16 v[10:13], v[138:141], v[212:215], v[10:13]
	s_setprio 0
	s_setprio 1
	v_mfma_f32_16x16x32_bf16 v[54:57], v[142:145], v[166:169], v[54:57]
	v_mfma_f32_16x16x32_bf16 v[50:53], v[158:161], v[166:169], v[50:53]
	v_mfma_f32_16x16x32_bf16 v[38:41], v[142:145], v[174:177], v[38:41]
	v_mfma_f32_16x16x32_bf16 v[34:37], v[158:161], v[174:177], v[34:37]
	v_mfma_f32_16x16x32_bf16 v[22:25], v[142:145], v[182:185], v[22:25]
	v_mfma_f32_16x16x32_bf16 v[18:21], v[158:161], v[182:185], v[18:21]
	v_mfma_f32_16x16x32_bf16 v[6:9], v[142:145], v[208:211], v[6:9]
	v_mfma_f32_16x16x32_bf16 v[2:5], v[158:161], v[208:211], v[2:5]
	v_mfma_f32_16x16x32_bf16 v[54:57], v[146:149], v[170:173], v[54:57]
	v_mfma_f32_16x16x32_bf16 v[50:53], v[162:165], v[170:173], v[50:53]
	v_mfma_f32_16x16x32_bf16 v[38:41], v[146:149], v[178:181], v[38:41]
	v_mfma_f32_16x16x32_bf16 v[34:37], v[162:165], v[178:181], v[34:37]
	v_mfma_f32_16x16x32_bf16 v[22:25], v[146:149], v[186:189], v[22:25]
	v_mfma_f32_16x16x32_bf16 v[18:21], v[162:165], v[186:189], v[18:21]
	v_mfma_f32_16x16x32_bf16 v[6:9], v[146:149], v[212:215], v[6:9]
	v_mfma_f32_16x16x32_bf16 v[2:5], v[162:165], v[212:215], v[2:5]
	s_setprio 0
	s_add_i32 s84, s84, 2
	s_add_u32 s36, s36, 0x100
	s_addc_u32 s37, s37, 0
	s_add_u32 s4, s34, s36
	s_addc_u32 s5, s35, s37
	s_add_u32 s42, s4, 0x100
	s_addc_u32 s43, s5, 0
	s_add_u32 s40, s76, s36
	s_addc_u32 s41, s78, s37
	s_add_u32 s4, s4, 0x180
	s_addc_u32 s5, s5, 0
	s_add_i32 s85, 0, 0x10000
	s_add_i32 vcc_lo, 0, 0x14000
	s_cmp_gt_u32 s84, 61
	s_barrier
	s_cbranch_scc0 .Lg6ak_body
	s_and_b64 vcc, exec, s[20:21]
	s_cbranch_vccz .LBB0_918
	s_barrier

.Lg6bk_body:
	v_add_u32_e32 v146, s71, v229
	v_add_u32_e32 v162, s74, v229
	ds_read_b128 v[134:137], v146
	ds_read_b128 v[138:141], v146 offset:1024
	ds_read_b128 v[142:145], v146 offset:2048
	ds_read_b128 v[146:149], v146 offset:3072
	ds_read_b128 v[150:153], v162
	ds_read_b128 v[154:157], v162 offset:1024
	ds_read_b128 v[158:161], v162 offset:2048
	ds_read_b128 v[162:165], v162 offset:3072
	s_cmpk_eq_i32 s26, 0x1f00
	s_cselect_b32 s29, s65, s5
	s_cselect_b32 s28, s59, s4
	s_cselect_b32 s31, s17, s31
	s_cselect_b32 s30, s58, s30
	s_cselect_b32 s35, s19, s35
	s_cselect_b32 s34, s57, s34
	v_lshl_add_u64 v[194:195], v[122:123], 0, s[26:27]
	s_add_i32 m0, s37, 0xc000
	ds_read_b128 v[166:169], v231
	ds_read_b128 v[170:173], v231 offset:1024
	ds_read_b128 v[174:177], v231 offset:2048
	ds_read_b128 v[178:181], v231 offset:3072
	ds_read_b128 v[182:185], v231 offset:4096
	ds_read_b128 v[186:189], v231 offset:5120
	ds_read_b128 v[190:193], v231 offset:6144
	ds_read_b128 v[212:215], v231 offset:7168
	global_load_lds_dwordx4 v[194:195], off
	v_lshl_add_u64 v[194:195], v[124:125], 0, s[26:27]
	s_add_i32 m0, s37, 0xe000
	s_nop 0
	global_load_lds_dwordx4 v[194:195], off
	s_waitcnt vmcnt(8)
	s_waitcnt lgkmcnt(0)
	s_barrier
	s_setprio 1
	s_waitcnt lgkmcnt(0)
	v_mfma_f32_16x16x32_bf16 v[130:133], v[134:137], v[166:169], v[130:133]
	v_mfma_f32_16x16x32_bf16 v[126:129], v[142:145], v[166:169], v[126:129]
	v_mfma_f32_16x16x32_bf16 v[110:113], v[134:137], v[174:177], v[110:113]
	v_mfma_f32_16x16x32_bf16 v[106:109], v[142:145], v[174:177], v[106:109]
	v_mfma_f32_16x16x32_bf16 v[94:97], v[134:137], v[182:185], v[94:97]
	v_mfma_f32_16x16x32_bf16 v[90:93], v[142:145], v[182:185], v[90:93]
	v_mfma_f32_16x16x32_bf16 v[78:81], v[134:137], v[190:193], v[78:81]
	v_mfma_f32_16x16x32_bf16 v[74:77], v[142:145], v[190:193], v[74:77]
	v_mfma_f32_16x16x32_bf16 v[130:133], v[138:141], v[170:173], v[130:133]
	v_mfma_f32_16x16x32_bf16 v[126:129], v[146:149], v[170:173], v[126:129]
	v_mfma_f32_16x16x32_bf16 v[110:113], v[138:141], v[178:181], v[110:113]
	v_mfma_f32_16x16x32_bf16 v[106:109], v[146:149], v[178:181], v[106:109]
	v_mfma_f32_16x16x32_bf16 v[94:97], v[138:141], v[186:189], v[94:97]
	v_mfma_f32_16x16x32_bf16 v[90:93], v[146:149], v[186:189], v[90:93]
	v_mfma_f32_16x16x32_bf16 v[78:81], v[138:141], v[212:215], v[78:81]
	v_mfma_f32_16x16x32_bf16 v[74:77], v[146:149], v[212:215], v[74:77]
	s_setprio 0
	s_setprio 1
	v_mfma_f32_16x16x32_bf16 v[118:121], v[150:153], v[166:169], v[118:121]
	v_mfma_f32_16x16x32_bf16 v[114:117], v[158:161], v[166:169], v[114:117]
	v_mfma_f32_16x16x32_bf16 v[102:105], v[150:153], v[174:177], v[102:105]
	v_mfma_f32_16x16x32_bf16 v[98:101], v[158:161], v[174:177], v[98:101]
	v_mfma_f32_16x16x32_bf16 v[86:89], v[150:153], v[182:185], v[86:89]
	v_mfma_f32_16x16x32_bf16 v[82:85], v[158:161], v[182:185], v[82:85]
	v_mfma_f32_16x16x32_bf16 v[70:73], v[150:153], v[190:193], v[70:73]
	v_mfma_f32_16x16x32_bf16 v[66:69], v[158:161], v[190:193], v[66:69]
	v_mfma_f32_16x16x32_bf16 v[118:121], v[154:157], v[170:173], v[118:121]
	v_mfma_f32_16x16x32_bf16 v[114:117], v[162:165], v[170:173], v[114:117]
	v_mfma_f32_16x16x32_bf16 v[102:105], v[154:157], v[178:181], v[102:105]
	v_mfma_f32_16x16x32_bf16 v[98:101], v[162:165], v[178:181], v[98:101]
	v_mfma_f32_16x16x32_bf16 v[86:89], v[154:157], v[186:189], v[86:89]
	v_mfma_f32_16x16x32_bf16 v[82:85], v[162:165], v[186:189], v[82:85]
	v_mfma_f32_16x16x32_bf16 v[70:73], v[154:157], v[212:215], v[70:73]
	v_mfma_f32_16x16x32_bf16 v[66:69], v[162:165], v[212:215], v[66:69]
	s_setprio 0
	s_barrier
	s_add_i32 s4, s71, s36
	v_lshl_add_u64 v[194:195], s[30:31], 0, v[0:1]
	s_mov_b32 m0, s4
	ds_read_b128 v[166:169], v231 offset:16384
	ds_read_b128 v[170:173], v231 offset:17408
	ds_read_b128 v[174:177], v231 offset:18432
	ds_read_b128 v[178:181], v231 offset:19456
	ds_read_b128 v[182:185], v231 offset:20480
	ds_read_b128 v[186:189], v231 offset:21504
	ds_read_b128 v[190:193], v231 offset:22528
	ds_read_b128 v[212:215], v231 offset:23552
	global_load_lds_dwordx4 v[194:195], off
	s_add_i32 m0, s4, 0x2000
	s_add_u32 s72, s30, 0x100000
	v_lshl_add_u64 v[198:199], s[30:31], 0, v[202:203]
	s_addc_u32 s73, s31, 0
	s_add_i32 s4, s74, s36
	global_load_lds_dwordx4 v[198:199], off
	v_lshl_add_u64 v[216:217], s[72:73], 0, v[0:1]
	s_mov_b32 m0, s4
	s_nop 0
	global_load_lds_dwordx4 v[216:217], off
	v_lshl_add_u64 v[216:217], s[72:73], 0, v[202:203]
	s_add_i32 m0, s4, 0x2000
	s_nop 0
	global_load_lds_dwordx4 v[216:217], off
	v_lshl_add_u64 v[216:217], s[34:35], 0, v[206:207]
	s_mov_b32 m0, s37
	s_nop 0
	global_load_lds_dwordx4 v[216:217], off
	v_lshl_add_u64 v[216:217], s[34:35], 0, v[204:205]
	s_mov_b32 m0, s38
	s_nop 0
	global_load_lds_dwordx4 v[216:217], off
	s_waitcnt vmcnt(8)
	s_waitcnt lgkmcnt(0)
	s_barrier
	s_setprio 1
	s_waitcnt lgkmcnt(0)
	v_mfma_f32_16x16x32_bf16 v[62:65], v[134:137], v[166:169], v[62:65]
	v_mfma_f32_16x16x32_bf16 v[58:61], v[142:145], v[166:169], v[58:61]
	v_mfma_f32_16x16x32_bf16 v[46:49], v[134:137], v[174:177], v[46:49]
	v_mfma_f32_16x16x32_bf16 v[42:45], v[142:145], v[174:177], v[42:45]
	v_mfma_f32_16x16x32_bf16 v[30:33], v[134:137], v[182:185], v[30:33]
	v_mfma_f32_16x16x32_bf16 v[26:29], v[142:145], v[182:185], v[26:29]
	v_mfma_f32_16x16x32_bf16 v[14:17], v[134:137], v[190:193], v[14:17]
	v_mfma_f32_16x16x32_bf16 v[10:13], v[142:145], v[190:193], v[10:13]
	v_mfma_f32_16x16x32_bf16 v[62:65], v[138:141], v[170:173], v[62:65]
	v_mfma_f32_16x16x32_bf16 v[58:61], v[146:149], v[170:173], v[58:61]
	v_mfma_f32_16x16x32_bf16 v[46:49], v[138:141], v[178:181], v[46:49]
	v_mfma_f32_16x16x32_bf16 v[42:45], v[146:149], v[178:181], v[42:45]
	v_mfma_f32_16x16x32_bf16 v[30:33], v[138:141], v[186:189], v[30:33]
	v_mfma_f32_16x16x32_bf16 v[26:29], v[146:149], v[186:189], v[26:29]
	v_mfma_f32_16x16x32_bf16 v[14:17], v[138:141], v[212:215], v[14:17]
	v_mfma_f32_16x16x32_bf16 v[10:13], v[146:149], v[212:215], v[10:13]
	s_setprio 0
	s_setprio 1
	v_mfma_f32_16x16x32_bf16 v[54:57], v[150:153], v[166:169], v[54:57]
	v_mfma_f32_16x16x32_bf16 v[50:53], v[158:161], v[166:169], v[50:53]
	v_mfma_f32_16x16x32_bf16 v[38:41], v[150:153], v[174:177], v[38:41]
	v_mfma_f32_16x16x32_bf16 v[34:37], v[158:161], v[174:177], v[34:37]
	v_mfma_f32_16x16x32_bf16 v[22:25], v[150:153], v[182:185], v[22:25]
	v_mfma_f32_16x16x32_bf16 v[18:21], v[158:161], v[182:185], v[18:21]
	v_mfma_f32_16x16x32_bf16 v[6:9], v[150:153], v[190:193], v[6:9]
	v_mfma_f32_16x16x32_bf16 v[2:5], v[158:161], v[190:193], v[2:5]
	v_mfma_f32_16x16x32_bf16 v[54:57], v[154:157], v[170:173], v[54:57]
	v_mfma_f32_16x16x32_bf16 v[50:53], v[162:165], v[170:173], v[50:53]
	v_mfma_f32_16x16x32_bf16 v[38:41], v[154:157], v[178:181], v[38:41]
	v_mfma_f32_16x16x32_bf16 v[34:37], v[162:165], v[178:181], v[34:37]
	v_mfma_f32_16x16x32_bf16 v[22:25], v[154:157], v[186:189], v[22:25]
	v_mfma_f32_16x16x32_bf16 v[18:21], v[162:165], v[186:189], v[18:21]
	v_mfma_f32_16x16x32_bf16 v[6:9], v[154:157], v[212:215], v[6:9]
	v_mfma_f32_16x16x32_bf16 v[2:5], v[162:165], v[212:215], v[2:5]
	s_setprio 0
	s_barrier
	s_add_i32 s4, 0, 0x18000
	s_add_i32 s5, 0, 0x1c000
	v_add_u32_e32 v146, s4, v229
	v_add_u32_e32 v162, s5, v229
	ds_read_b128 v[134:137], v146
	ds_read_b128 v[138:141], v146 offset:1024
	ds_read_b128 v[142:145], v146 offset:2048
	ds_read_b128 v[146:149], v146 offset:3072
	ds_read_b128 v[150:153], v162
	ds_read_b128 v[154:157], v162 offset:1024
	ds_read_b128 v[158:161], v162 offset:2048
	ds_read_b128 v[162:165], v162 offset:3072
	s_add_u32 s34, s34, 0x100000
	s_addc_u32 s35, s35, 0
	s_mov_b32 m0, s39
	v_lshl_add_u64 v[216:217], s[34:35], 0, v[206:207]
	ds_read_b128 v[166:169], v231 offset:32768
	ds_read_b128 v[170:173], v231 offset:33792
	ds_read_b128 v[174:177], v231 offset:34816
	ds_read_b128 v[178:181], v231 offset:35840
	ds_read_b128 v[182:185], v231 offset:36864
	ds_read_b128 v[186:189], v231 offset:37888
	ds_read_b128 v[190:193], v231 offset:38912
	ds_read_b128 v[212:215], v231 offset:39936
	global_load_lds_dwordx4 v[216:217], off
	v_lshl_add_u64 v[216:217], s[34:35], 0, v[204:205]
	s_mov_b32 m0, s40
	s_nop 0
	global_load_lds_dwordx4 v[216:217], off
	s_waitcnt vmcnt(8)
	s_waitcnt lgkmcnt(0)
	s_barrier
	s_setprio 1
	s_waitcnt lgkmcnt(0)
	v_mfma_f32_16x16x32_bf16 v[130:133], v[134:137], v[166:169], v[130:133]
	v_mfma_f32_16x16x32_bf16 v[126:129], v[142:145], v[166:169], v[126:129]
	v_mfma_f32_16x16x32_bf16 v[110:113], v[134:137], v[174:177], v[110:113]
	v_mfma_f32_16x16x32_bf16 v[106:109], v[142:145], v[174:177], v[106:109]
	v_mfma_f32_16x16x32_bf16 v[94:97], v[134:137], v[182:185], v[94:97]
	v_mfma_f32_16x16x32_bf16 v[90:93], v[142:145], v[182:185], v[90:93]
	v_mfma_f32_16x16x32_bf16 v[78:81], v[134:137], v[190:193], v[78:81]
	v_mfma_f32_16x16x32_bf16 v[74:77], v[142:145], v[190:193], v[74:77]
	v_mfma_f32_16x16x32_bf16 v[130:133], v[138:141], v[170:173], v[130:133]
	v_mfma_f32_16x16x32_bf16 v[126:129], v[146:149], v[170:173], v[126:129]
	v_mfma_f32_16x16x32_bf16 v[110:113], v[138:141], v[178:181], v[110:113]
	v_mfma_f32_16x16x32_bf16 v[106:109], v[146:149], v[178:181], v[106:109]
	v_mfma_f32_16x16x32_bf16 v[94:97], v[138:141], v[186:189], v[94:97]
	v_mfma_f32_16x16x32_bf16 v[90:93], v[146:149], v[186:189], v[90:93]
	v_mfma_f32_16x16x32_bf16 v[78:81], v[138:141], v[212:215], v[78:81]
	v_mfma_f32_16x16x32_bf16 v[74:77], v[146:149], v[212:215], v[74:77]
	s_setprio 0
	s_setprio 1
	v_mfma_f32_16x16x32_bf16 v[118:121], v[150:153], v[166:169], v[118:121]
	v_mfma_f32_16x16x32_bf16 v[114:117], v[158:161], v[166:169], v[114:117]
	v_mfma_f32_16x16x32_bf16 v[102:105], v[150:153], v[174:177], v[102:105]
	v_mfma_f32_16x16x32_bf16 v[98:101], v[158:161], v[174:177], v[98:101]
	v_mfma_f32_16x16x32_bf16 v[86:89], v[150:153], v[182:185], v[86:89]
	v_mfma_f32_16x16x32_bf16 v[82:85], v[158:161], v[182:185], v[82:85]
	v_mfma_f32_16x16x32_bf16 v[70:73], v[150:153], v[190:193], v[70:73]
	v_mfma_f32_16x16x32_bf16 v[66:69], v[158:161], v[190:193], v[66:69]
	v_mfma_f32_16x16x32_bf16 v[118:121], v[154:157], v[170:173], v[118:121]
	v_mfma_f32_16x16x32_bf16 v[114:117], v[162:165], v[170:173], v[114:117]
	v_mfma_f32_16x16x32_bf16 v[102:105], v[154:157], v[178:181], v[102:105]
	v_mfma_f32_16x16x32_bf16 v[98:101], v[162:165], v[178:181], v[98:101]
	v_mfma_f32_16x16x32_bf16 v[86:89], v[154:157], v[186:189], v[86:89]
	v_mfma_f32_16x16x32_bf16 v[82:85], v[162:165], v[186:189], v[82:85]
	v_mfma_f32_16x16x32_bf16 v[70:73], v[154:157], v[212:215], v[70:73]
	v_mfma_f32_16x16x32_bf16 v[66:69], v[162:165], v[212:215], v[66:69]
	s_setprio 0
	s_barrier
	s_add_i32 s4, s4, s36
	v_lshl_add_u64 v[194:195], v[194:195], 0, s[90:91]
	s_mov_b32 m0, s4
	ds_read_b128 v[166:169], v231 offset:49152
	ds_read_b128 v[170:173], v231 offset:50176
	ds_read_b128 v[174:177], v231 offset:51200
	ds_read_b128 v[178:181], v231 offset:52224
	ds_read_b128 v[182:185], v231 offset:53248
	ds_read_b128 v[186:189], v231 offset:54272
	ds_read_b128 v[190:193], v231 offset:55296
	ds_read_b128 v[212:215], v231 offset:56320
	global_load_lds_dwordx4 v[194:195], off
	s_add_i32 m0, s4, 0x2000
	s_add_u32 s30, s30, 0x100080
	v_lshl_add_u64 v[194:195], v[198:199], 0, s[90:91]
	s_addc_u32 s31, s31, 0
	s_add_i32 s4, s5, s36
	global_load_lds_dwordx4 v[194:195], off
	v_lshl_add_u64 v[194:195], s[30:31], 0, v[0:1]
	s_mov_b32 m0, s4
	s_nop 0
	global_load_lds_dwordx4 v[194:195], off
	v_lshl_add_u64 v[194:195], s[30:31], 0, v[202:203]
	s_add_i32 m0, s4, 0x2000
	s_nop 0
	global_load_lds_dwordx4 v[194:195], off
	v_lshl_add_u64 v[194:195], s[28:29], 0, v[206:207]
	s_mov_b32 m0, s41
	s_nop 0
	global_load_lds_dwordx4 v[194:195], off
	v_lshl_add_u64 v[194:195], s[28:29], 0, v[204:205]
	s_mov_b32 m0, s42
	s_nop 0
	global_load_lds_dwordx4 v[194:195], off
	s_waitcnt vmcnt(8)
	s_waitcnt lgkmcnt(0)
	s_barrier
	s_setprio 1
	s_waitcnt lgkmcnt(0)
	v_mfma_f32_16x16x32_bf16 v[62:65], v[134:137], v[166:169], v[62:65]
	v_mfma_f32_16x16x32_bf16 v[58:61], v[142:145], v[166:169], v[58:61]
	v_mfma_f32_16x16x32_bf16 v[46:49], v[134:137], v[174:177], v[46:49]
	v_mfma_f32_16x16x32_bf16 v[42:45], v[142:145], v[174:177], v[42:45]
	v_mfma_f32_16x16x32_bf16 v[30:33], v[134:137], v[182:185], v[30:33]
	v_mfma_f32_16x16x32_bf16 v[26:29], v[142:145], v[182:185], v[26:29]
	v_mfma_f32_16x16x32_bf16 v[14:17], v[134:137], v[190:193], v[14:17]
	v_mfma_f32_16x16x32_bf16 v[10:13], v[142:145], v[190:193], v[10:13]
	v_mfma_f32_16x16x32_bf16 v[62:65], v[138:141], v[170:173], v[62:65]
	v_mfma_f32_16x16x32_bf16 v[58:61], v[146:149], v[170:173], v[58:61]
	v_mfma_f32_16x16x32_bf16 v[46:49], v[138:141], v[178:181], v[46:49]
	v_mfma_f32_16x16x32_bf16 v[42:45], v[146:149], v[178:181], v[42:45]
	v_mfma_f32_16x16x32_bf16 v[30:33], v[138:141], v[186:189], v[30:33]
	v_mfma_f32_16x16x32_bf16 v[26:29], v[146:149], v[186:189], v[26:29]
	v_mfma_f32_16x16x32_bf16 v[14:17], v[138:141], v[212:215], v[14:17]
	v_mfma_f32_16x16x32_bf16 v[10:13], v[146:149], v[212:215], v[10:13]
	s_setprio 0
	s_setprio 1
	v_mfma_f32_16x16x32_bf16 v[54:57], v[150:153], v[166:169], v[54:57]
	v_mfma_f32_16x16x32_bf16 v[50:53], v[158:161], v[166:169], v[50:53]
	v_mfma_f32_16x16x32_bf16 v[38:41], v[150:153], v[174:177], v[38:41]
	v_mfma_f32_16x16x32_bf16 v[34:37], v[158:161], v[174:177], v[34:37]
	v_mfma_f32_16x16x32_bf16 v[22:25], v[150:153], v[182:185], v[22:25]
	v_mfma_f32_16x16x32_bf16 v[18:21], v[158:161], v[182:185], v[18:21]
	v_mfma_f32_16x16x32_bf16 v[6:9], v[150:153], v[190:193], v[6:9]
	v_mfma_f32_16x16x32_bf16 v[2:5], v[158:161], v[190:193], v[2:5]
	v_mfma_f32_16x16x32_bf16 v[54:57], v[154:157], v[170:173], v[54:57]
	v_mfma_f32_16x16x32_bf16 v[50:53], v[162:165], v[170:173], v[50:53]
	v_mfma_f32_16x16x32_bf16 v[38:41], v[154:157], v[178:181], v[38:41]
	v_mfma_f32_16x16x32_bf16 v[34:37], v[162:165], v[178:181], v[34:37]
	v_mfma_f32_16x16x32_bf16 v[22:25], v[154:157], v[186:189], v[22:25]
	v_mfma_f32_16x16x32_bf16 v[18:21], v[162:165], v[186:189], v[18:21]
	v_mfma_f32_16x16x32_bf16 v[6:9], v[154:157], v[212:215], v[6:9]
	v_mfma_f32_16x16x32_bf16 v[2:5], v[162:165], v[212:215], v[2:5]
	s_setprio 0
	s_add_i32 s70, s70, 2
	s_add_u32 s26, s26, 0x100
	s_addc_u32 s27, s27, 0
	s_add_u32 s4, s24, s26
	s_addc_u32 s5, s25, s27
	s_add_u32 s34, s4, 0x100
	s_addc_u32 s35, s5, 0
	s_add_u32 s30, s68, s26
	s_addc_u32 s31, s69, s27
	s_add_u32 s4, s4, 0x180
	s_addc_u32 s5, s5, 0
	s_add_i32 s71, 0, 0x10000
	s_add_i32 s74, 0, 0x14000
	s_cmp_gt_u32 s70, 61
	s_barrier
	s_cbranch_scc0 .Lg6bk_body
	s_and_b64 vcc, exec, s[14:15]
	s_cbranch_vccz .LBB0_956
	s_barrier
